# GEMM K-loops: s_setprio 1 moved before the opening barrier and s_setprio 0 after the closing barrier, so each compute segment between barriers is 32 bare MFMAs
# baseline (speedup 1.0000x reference)
; #define PG8_STAGE(bufoff, gbase, voff) do { _Pragma("unroll") for (int _i = 0; _i < 2; ++_i) \
;         __builtin_amdgcn_global_load_lds((const unsigned*)((const char*)(gbase) + (voff)[_i]), (LAS unsigned*)(lds + (bufoff) + ldsw + _i * 8192), 16, 0, 0); } while (0)
; #define PG8_LDA(dst, b, h) do { _Pragma("unroll") for (int m = 0; m < 4; ++m) _Pragma("unroll") for (int k = 0; k < 2; ++k) dst[m][k] = *(const LAS bf16x8*)(lds + PG8_SA(b, h) + aoff + m * 2048 + k * 1024); } while (0)
; #define PG8_LDB(dst, b, h) do { _Pragma("unroll") for (int n = 0; n < 2; ++n) _Pragma("unroll") for (int k = 0; k < 2; ++k) dst[n][k] = *(const LAS bf16x8*)(lds + PG8_SB(b, h) + boff + n * 2048 + k * 1024); } while (0)
; #define PG8_MMA(ai, bj, At, Bt) do { __builtin_amdgcn_s_setprio(1); _Pragma("unroll") for (int m = 0; m < 4; ++m) _Pragma("unroll") for (int n = 0; n < 2; ++n) _Pragma("unroll") for (int k = 0; k < 2; ++k) \
;         acc[ai][bj][m][n] = __builtin_amdgcn_mfma_f32_16x16x32_bf16(Bt[n][k], At[m][k], acc[ai][bj][m][n], 0, 0, 0); __builtin_amdgcn_s_setprio(0); } while (0)
; #define PG8_WAIT_V(n) asm volatile("s_waitcnt vmcnt(" #n ")" ::: "memory")
; #define PG8_WAIT_L(n) asm volatile("s_waitcnt lgkmcnt(" #n ")" ::: "memory")
; #define PG8_BAR __builtin_amdgcn_s_barrier()
; template <class Epi, class Sched = StaticOrder, class EpiSub = NoSub, bool FAST = false>
; __device__ __forceinline__ void gemm_phase(LAS unsigned char* lds, const Gemm g, const Sched& S, const Epi& E, const EpiSub& ES = EpiSub()) {
;     ...
;             const bool last = (t == nt - 2);
;             const char* a1 = cA + (size_t)(t + 1) * kstep;
;             const char* a2 = last ? nA : cA + (size_t)(t + 2) * kstep; const char* b2 = last ? nB : cB + (size_t)(t + 2) * kstep;
;             const char* a3 = a2 + kstep; const char* b3 = b2 + kstep;
;             if constexpr (FAST && PG8_SP2) {
;             PG8_LDB(B0, 0, 0); PG8_LDB(B1, 0, 1); PG8_SCHED; PG8_LDA(At, 0, 0); PG8_STAGE(PG8_SA(1, 1), a1 + hstepA, voffA);
;             PG8_WAIT_V(8); PG8_WAIT_L(0); PG8_BAR; PG8_MMA(0, 0, At, B0); PG8_MMA(0, 1, At, B1); PG8_BAR; PG8_SCHED;
;             PG8_LDA(At, 0, 1); PG8_STAGE(PG8_SB(0, 0), b2, voffB); PG8_STAGE(PG8_SB(0, 1), b2 + hstepB, voffB); PG8_STAGE(PG8_SA(0, 0), a2, voffA);
;             PG8_WAIT_V(8); PG8_WAIT_L(0); PG8_BAR; PG8_MMA(1, 0, At, B0); PG8_MMA(1, 1, At, B1); PG8_BAR; PG8_SCHED;
.LBB0_216:
	ds_read_b128 v[154:157], v150
	ds_read_b128 v[158:161], v150 offset:1024
	ds_read_b128 v[162:165], v150 offset:2048
	ds_read_b128 v[166:169], v150 offset:3072
	ds_read_b128 v[170:173], v151
	ds_read_b128 v[174:177], v151 offset:1024
	ds_read_b128 v[178:181], v151 offset:2048
	ds_read_b128 v[182:185], v151 offset:3072
	s_add_u32 s24, s22, 0xfff80080
	s_addc_u32 s25, s23, -1
	s_cmp_eq_u32 s50, 28
	s_cselect_b32 s27, s2, s25
	s_cselect_b32 s26, s3, s24
	s_cselect_b32 s25, s13, s49
	s_cselect_b32 s24, s15, s48
	v_lshl_add_u64 v[144:145], s[22:23], 0, v[136:137]
	s_add_i32 m0, s21, 0xc000
	ds_read_b128 v[186:189], v152
	ds_read_b128 v[194:197], v152 offset:1024
	ds_read_b128 v[198:201], v152 offset:2048
	ds_read_b128 v[202:205], v152 offset:3072
	ds_read_b128 v[206:209], v152 offset:4096
	ds_read_b128 v[210:213], v152 offset:5120
	ds_read_b128 v[214:217], v152 offset:6144
	ds_read_b128 v[218:221], v152 offset:7168
	global_load_lds_dwordx4 v[144:145], off
	v_lshl_add_u64 v[144:145], s[22:23], 0, v[138:139]
	s_add_i32 m0, s21, 0xe000
	s_nop 0
	global_load_lds_dwordx4 v[144:145], off
	s_waitcnt vmcnt(8)
	s_waitcnt lgkmcnt(0)
	s_setprio 1
	s_barrier
	v_mfma_f32_16x16x32_bf16 v[124:127], v[154:157], v[186:189], v[124:127]
	v_mfma_f32_16x16x32_bf16 v[120:123], v[162:165], v[186:189], v[120:123]
	v_mfma_f32_16x16x32_bf16 v[116:119], v[154:157], v[198:201], v[116:119]
	v_mfma_f32_16x16x32_bf16 v[108:111], v[162:165], v[198:201], v[108:111]
	v_mfma_f32_16x16x32_bf16 v[100:103], v[154:157], v[206:209], v[100:103]
	v_mfma_f32_16x16x32_bf16 v[92:95], v[162:165], v[206:209], v[92:95]
	v_mfma_f32_16x16x32_bf16 v[84:87], v[154:157], v[214:217], v[84:87]
	v_mfma_f32_16x16x32_bf16 v[76:79], v[162:165], v[214:217], v[76:79]
	v_mfma_f32_16x16x32_bf16 v[124:127], v[158:161], v[194:197], v[124:127]
	v_mfma_f32_16x16x32_bf16 v[120:123], v[166:169], v[194:197], v[120:123]
	v_mfma_f32_16x16x32_bf16 v[116:119], v[158:161], v[202:205], v[116:119]
	v_mfma_f32_16x16x32_bf16 v[108:111], v[166:169], v[202:205], v[108:111]
	v_mfma_f32_16x16x32_bf16 v[100:103], v[158:161], v[210:213], v[100:103]
	v_mfma_f32_16x16x32_bf16 v[92:95], v[166:169], v[210:213], v[92:95]
	v_mfma_f32_16x16x32_bf16 v[84:87], v[158:161], v[218:221], v[84:87]
	v_mfma_f32_16x16x32_bf16 v[76:79], v[166:169], v[218:221], v[76:79]
	v_mfma_f32_16x16x32_bf16 v[112:115], v[170:173], v[186:189], v[112:115]
	v_mfma_f32_16x16x32_bf16 v[104:107], v[178:181], v[186:189], v[104:107]
	v_mfma_f32_16x16x32_bf16 v[96:99], v[170:173], v[198:201], v[96:99]
	v_mfma_f32_16x16x32_bf16 v[88:91], v[178:181], v[198:201], v[88:91]
	v_mfma_f32_16x16x32_bf16 v[80:83], v[170:173], v[206:209], v[80:83]
	v_mfma_f32_16x16x32_bf16 v[72:75], v[178:181], v[206:209], v[72:75]
	v_mfma_f32_16x16x32_bf16 v[68:71], v[170:173], v[214:217], v[68:71]
	v_mfma_f32_16x16x32_bf16 v[64:67], v[178:181], v[214:217], v[64:67]
	v_mfma_f32_16x16x32_bf16 v[112:115], v[174:177], v[194:197], v[112:115]
	v_mfma_f32_16x16x32_bf16 v[104:107], v[182:185], v[194:197], v[104:107]
	v_mfma_f32_16x16x32_bf16 v[96:99], v[174:177], v[202:205], v[96:99]
	v_mfma_f32_16x16x32_bf16 v[88:91], v[182:185], v[202:205], v[88:91]
	v_mfma_f32_16x16x32_bf16 v[80:83], v[174:177], v[210:213], v[80:83]
	v_mfma_f32_16x16x32_bf16 v[72:75], v[182:185], v[210:213], v[72:75]
	v_mfma_f32_16x16x32_bf16 v[68:71], v[174:177], v[218:221], v[68:71]
	v_mfma_f32_16x16x32_bf16 v[64:67], v[182:185], v[218:221], v[64:67]
	s_barrier
	s_setprio 0
	s_add_i32 s51, s41, s30
	v_lshl_add_u64 v[144:145], s[24:25], 0, v[130:131]
	s_mov_b32 m0, s51
	ds_read_b128 v[186:189], v152 offset:16384
	ds_read_b128 v[194:197], v152 offset:17408
	ds_read_b128 v[198:201], v152 offset:18432
	ds_read_b128 v[202:205], v152 offset:19456
	ds_read_b128 v[206:209], v152 offset:20480
	ds_read_b128 v[210:213], v152 offset:21504
	ds_read_b128 v[214:217], v152 offset:22528
	ds_read_b128 v[218:221], v152 offset:23552
	global_load_lds_dwordx4 v[144:145], off
	s_add_i32 m0, s51, 0x2000
	s_add_u32 s68, s24, 0x80000
	v_lshl_add_u64 v[190:191], s[24:25], 0, v[134:135]
	s_addc_u32 s69, s25, 0
	s_add_i32 s51, s42, s30
	global_load_lds_dwordx4 v[190:191], off
	v_lshl_add_u64 v[222:223], s[68:69], 0, v[130:131]
	s_mov_b32 m0, s51
	v_lshl_add_u64 v[224:225], s[26:27], 0, v[132:133]
	global_load_lds_dwordx4 v[222:223], off
	v_lshl_add_u64 v[222:223], s[68:69], 0, v[134:135]
	s_add_i32 m0, s51, 0x2000
	s_nop 0
	global_load_lds_dwordx4 v[222:223], off
	v_lshl_add_u64 v[222:223], s[26:27], 0, v[128:129]
	s_mov_b32 m0, s21
	s_nop 0
	global_load_lds_dwordx4 v[222:223], off
	s_mov_b32 m0, s34
	s_nop 0
	global_load_lds_dwordx4 v[224:225], off
	s_waitcnt vmcnt(8)
	s_waitcnt lgkmcnt(0)
	s_setprio 1
	s_barrier
; #define PG8_STAGE(bufoff, gbase, voff) do { _Pragma("unroll") for (int _i = 0; _i < 2; ++_i) \
;         __builtin_amdgcn_global_load_lds((const unsigned*)((const char*)(gbase) + (voff)[_i]), (LAS unsigned*)(lds + (bufoff) + ldsw + _i * 8192), 16, 0, 0); } while (0)
; #define PG8_LDA(dst, b, h) do { _Pragma("unroll") for (int m = 0; m < 4; ++m) _Pragma("unroll") for (int k = 0; k < 2; ++k) dst[m][k] = *(const LAS bf16x8*)(lds + PG8_SA(b, h) + aoff + m * 2048 + k * 1024); } while (0)
; #define PG8_LDB(dst, b, h) do { _Pragma("unroll") for (int n = 0; n < 2; ++n) _Pragma("unroll") for (int k = 0; k < 2; ++k) dst[n][k] = *(const LAS bf16x8*)(lds + PG8_SB(b, h) + boff + n * 2048 + k * 1024); } while (0)
; #define PG8_MMA(ai, bj, At, Bt) do { __builtin_amdgcn_s_setprio(1); _Pragma("unroll") for (int m = 0; m < 4; ++m) _Pragma("unroll") for (int n = 0; n < 2; ++n) _Pragma("unroll") for (int k = 0; k < 2; ++k) \
;         acc[ai][bj][m][n] = __builtin_amdgcn_mfma_f32_16x16x32_bf16(Bt[n][k], At[m][k], acc[ai][bj][m][n], 0, 0, 0); __builtin_amdgcn_s_setprio(0); } while (0)
; #define PG8_WAIT_V(n) asm volatile("s_waitcnt vmcnt(" #n ")" ::: "memory")
; #define PG8_WAIT_L(n) asm volatile("s_waitcnt lgkmcnt(" #n ")" ::: "memory")
; #define PG8_BAR __builtin_amdgcn_s_barrier()
; #define PG8_SCHED __builtin_amdgcn_sched_barrier(0)
; template <class Epi, class Sched = StaticOrder, class EpiSub = NoSub, bool FAST = false>
; __device__ __forceinline__ void gemm_phase(LAS unsigned char* lds, const Gemm g, const Sched& S, const Epi& E, const EpiSub& ES = EpiSub()) {
;     ...
;             PG8_WAIT_V(8); PG8_WAIT_L(0); PG8_BAR; PG8_MMA(1, 0, At, B0); PG8_MMA(1, 1, At, B1); PG8_BAR; PG8_SCHED;
;             PG8_LDB(B0, 1, 0); PG8_LDB(B1, 1, 1); PG8_SCHED; PG8_LDA(At, 1, 0); PG8_STAGE(PG8_SA(0, 1), a2 + hstepA, voffA);
;             PG8_WAIT_V(8); PG8_WAIT_L(0); PG8_BAR; PG8_MMA(0, 0, At, B0); PG8_MMA(0, 1, At, B1); PG8_BAR; PG8_SCHED;
	v_mfma_f32_16x16x32_bf16 v[60:63], v[154:157], v[186:189], v[60:63]
	v_mfma_f32_16x16x32_bf16 v[56:59], v[162:165], v[186:189], v[56:59]
	v_mfma_f32_16x16x32_bf16 v[52:55], v[154:157], v[198:201], v[52:55]
	v_mfma_f32_16x16x32_bf16 v[44:47], v[162:165], v[198:201], v[44:47]
	v_mfma_f32_16x16x32_bf16 v[36:39], v[154:157], v[206:209], v[36:39]
	v_mfma_f32_16x16x32_bf16 v[28:31], v[162:165], v[206:209], v[28:31]
	v_mfma_f32_16x16x32_bf16 v[20:23], v[154:157], v[214:217], v[20:23]
	v_mfma_f32_16x16x32_bf16 v[12:15], v[162:165], v[214:217], v[12:15]
	v_mfma_f32_16x16x32_bf16 v[60:63], v[158:161], v[194:197], v[60:63]
	v_mfma_f32_16x16x32_bf16 v[56:59], v[166:169], v[194:197], v[56:59]
	v_mfma_f32_16x16x32_bf16 v[52:55], v[158:161], v[202:205], v[52:55]
	v_mfma_f32_16x16x32_bf16 v[44:47], v[166:169], v[202:205], v[44:47]
	v_mfma_f32_16x16x32_bf16 v[36:39], v[158:161], v[210:213], v[36:39]
	v_mfma_f32_16x16x32_bf16 v[28:31], v[166:169], v[210:213], v[28:31]
	v_mfma_f32_16x16x32_bf16 v[20:23], v[158:161], v[218:221], v[20:23]
	v_mfma_f32_16x16x32_bf16 v[12:15], v[166:169], v[218:221], v[12:15]
	v_mfma_f32_16x16x32_bf16 v[48:51], v[170:173], v[186:189], v[48:51]
	v_mfma_f32_16x16x32_bf16 v[40:43], v[178:181], v[186:189], v[40:43]
	v_mfma_f32_16x16x32_bf16 v[32:35], v[170:173], v[198:201], v[32:35]
	v_mfma_f32_16x16x32_bf16 v[24:27], v[178:181], v[198:201], v[24:27]
	v_mfma_f32_16x16x32_bf16 v[16:19], v[170:173], v[206:209], v[16:19]
	v_mfma_f32_16x16x32_bf16 v[8:11], v[178:181], v[206:209], v[8:11]
	v_mfma_f32_16x16x32_bf16 v[4:7], v[170:173], v[214:217], v[4:7]
	v_mfma_f32_16x16x32_bf16 v[0:3], v[178:181], v[214:217], v[0:3]
	v_mfma_f32_16x16x32_bf16 v[48:51], v[174:177], v[194:197], v[48:51]
	v_mfma_f32_16x16x32_bf16 v[40:43], v[182:185], v[194:197], v[40:43]
	v_mfma_f32_16x16x32_bf16 v[32:35], v[174:177], v[202:205], v[32:35]
	v_mfma_f32_16x16x32_bf16 v[24:27], v[182:185], v[202:205], v[24:27]
	v_mfma_f32_16x16x32_bf16 v[16:19], v[174:177], v[210:213], v[16:19]
	v_mfma_f32_16x16x32_bf16 v[8:11], v[182:185], v[210:213], v[8:11]
	v_mfma_f32_16x16x32_bf16 v[4:7], v[174:177], v[218:221], v[4:7]
	v_mfma_f32_16x16x32_bf16 v[0:3], v[182:185], v[218:221], v[0:3]
	s_barrier
	s_setprio 0
	s_add_i32 s51, 0, 0x18000
	v_add_u32_e32 v153, s51, v148
	s_add_i32 s68, 0, 0x1c000
	ds_read_b128 v[154:157], v153
	ds_read_b128 v[158:161], v153 offset:1024
	ds_read_b128 v[162:165], v153 offset:2048
	ds_read_b128 v[166:169], v153 offset:3072
	v_add_u32_e32 v153, s68, v148
	ds_read_b128 v[170:173], v153
	ds_read_b128 v[174:177], v153 offset:1024
	ds_read_b128 v[178:181], v153 offset:2048
	ds_read_b128 v[182:185], v153 offset:3072
	s_add_u32 s26, s26, 0x80000
	s_addc_u32 s27, s27, 0
	s_mov_b32 m0, s35
	v_lshl_add_u64 v[226:227], s[26:27], 0, v[128:129]
	ds_read_b128 v[186:189], v152 offset:32768
	ds_read_b128 v[194:197], v152 offset:33792
	ds_read_b128 v[198:201], v152 offset:34816
	ds_read_b128 v[202:205], v152 offset:35840
	ds_read_b128 v[206:209], v152 offset:36864
	ds_read_b128 v[210:213], v152 offset:37888
	ds_read_b128 v[214:217], v152 offset:38912
	ds_read_b128 v[218:221], v152 offset:39936
	global_load_lds_dwordx4 v[226:227], off
	v_lshl_add_u64 v[226:227], s[26:27], 0, v[132:133]
	s_mov_b32 m0, s36
	s_nop 0
	global_load_lds_dwordx4 v[226:227], off
	s_waitcnt vmcnt(8)
	s_waitcnt lgkmcnt(0)
	s_setprio 1
	s_barrier
	v_mfma_f32_16x16x32_bf16 v[124:127], v[154:157], v[186:189], v[124:127]
	v_mfma_f32_16x16x32_bf16 v[120:123], v[162:165], v[186:189], v[120:123]
	v_mfma_f32_16x16x32_bf16 v[116:119], v[154:157], v[198:201], v[116:119]
	v_mfma_f32_16x16x32_bf16 v[108:111], v[162:165], v[198:201], v[108:111]
	v_mfma_f32_16x16x32_bf16 v[100:103], v[154:157], v[206:209], v[100:103]
	v_mfma_f32_16x16x32_bf16 v[92:95], v[162:165], v[206:209], v[92:95]
	v_mfma_f32_16x16x32_bf16 v[84:87], v[154:157], v[214:217], v[84:87]
	v_mfma_f32_16x16x32_bf16 v[76:79], v[162:165], v[214:217], v[76:79]
	v_mfma_f32_16x16x32_bf16 v[124:127], v[158:161], v[194:197], v[124:127]
	v_mfma_f32_16x16x32_bf16 v[120:123], v[166:169], v[194:197], v[120:123]
	v_mfma_f32_16x16x32_bf16 v[116:119], v[158:161], v[202:205], v[116:119]
	v_mfma_f32_16x16x32_bf16 v[108:111], v[166:169], v[202:205], v[108:111]
	v_mfma_f32_16x16x32_bf16 v[100:103], v[158:161], v[210:213], v[100:103]
	v_mfma_f32_16x16x32_bf16 v[92:95], v[166:169], v[210:213], v[92:95]
	v_mfma_f32_16x16x32_bf16 v[84:87], v[158:161], v[218:221], v[84:87]
	v_mfma_f32_16x16x32_bf16 v[76:79], v[166:169], v[218:221], v[76:79]
	v_mfma_f32_16x16x32_bf16 v[112:115], v[170:173], v[186:189], v[112:115]
	v_mfma_f32_16x16x32_bf16 v[104:107], v[178:181], v[186:189], v[104:107]
	v_mfma_f32_16x16x32_bf16 v[96:99], v[170:173], v[198:201], v[96:99]
	v_mfma_f32_16x16x32_bf16 v[88:91], v[178:181], v[198:201], v[88:91]
	v_mfma_f32_16x16x32_bf16 v[80:83], v[170:173], v[206:209], v[80:83]
	v_mfma_f32_16x16x32_bf16 v[72:75], v[178:181], v[206:209], v[72:75]
	v_mfma_f32_16x16x32_bf16 v[68:71], v[170:173], v[214:217], v[68:71]
	v_mfma_f32_16x16x32_bf16 v[64:67], v[178:181], v[214:217], v[64:67]
	v_mfma_f32_16x16x32_bf16 v[112:115], v[174:177], v[194:197], v[112:115]
	v_mfma_f32_16x16x32_bf16 v[104:107], v[182:185], v[194:197], v[104:107]
	v_mfma_f32_16x16x32_bf16 v[96:99], v[174:177], v[202:205], v[96:99]
	v_mfma_f32_16x16x32_bf16 v[88:91], v[182:185], v[202:205], v[88:91]
	v_mfma_f32_16x16x32_bf16 v[80:83], v[174:177], v[210:213], v[80:83]
	v_mfma_f32_16x16x32_bf16 v[72:75], v[182:185], v[210:213], v[72:75]
	v_mfma_f32_16x16x32_bf16 v[68:71], v[174:177], v[218:221], v[68:71]
	v_mfma_f32_16x16x32_bf16 v[64:67], v[182:185], v[218:221], v[64:67]
	s_barrier
; #define PG8_STAGE(bufoff, gbase, voff) do { _Pragma("unroll") for (int _i = 0; _i < 2; ++_i) \
;         __builtin_amdgcn_global_load_lds((const unsigned*)((const char*)(gbase) + (voff)[_i]), (LAS unsigned*)(lds + (bufoff) + ldsw + _i * 8192), 16, 0, 0); } while (0)
; #define PG8_LDA(dst, b, h) do { _Pragma("unroll") for (int m = 0; m < 4; ++m) _Pragma("unroll") for (int k = 0; k < 2; ++k) dst[m][k] = *(const LAS bf16x8*)(lds + PG8_SA(b, h) + aoff + m * 2048 + k * 1024); } while (0)
; #define PG8_MMA(ai, bj, At, Bt) do { __builtin_amdgcn_s_setprio(1); _Pragma("unroll") for (int m = 0; m < 4; ++m) _Pragma("unroll") for (int n = 0; n < 2; ++n) _Pragma("unroll") for (int k = 0; k < 2; ++k) \
;         acc[ai][bj][m][n] = __builtin_amdgcn_mfma_f32_16x16x32_bf16(Bt[n][k], At[m][k], acc[ai][bj][m][n], 0, 0, 0); __builtin_amdgcn_s_setprio(0); } while (0)
; #define PG8_WAIT_V(n) asm volatile("s_waitcnt vmcnt(" #n ")" ::: "memory")
; #define PG8_WAIT_L(n) asm volatile("s_waitcnt lgkmcnt(" #n ")" ::: "memory")
; #define PG8_BAR __builtin_amdgcn_s_barrier()
; #define PG8_SCHED __builtin_amdgcn_sched_barrier(0)
; template <class Epi, class Sched = StaticOrder, class EpiSub = NoSub, bool FAST = false>
; __device__ __forceinline__ void gemm_phase(LAS unsigned char* lds, const Gemm g, const Sched& S, const Epi& E, const EpiSub& ES = EpiSub()) {
;     ...
;         for (int t = 0; t < nt; t += 2) {
;     ...
;             PG8_LDA(At, 1, 1); PG8_STAGE(PG8_SB(1, 0), b3, voffB); PG8_STAGE(PG8_SB(1, 1), b3 + hstepB, voffB); PG8_STAGE(PG8_SA(1, 0), a3, voffA);
;             PG8_WAIT_V(8); PG8_WAIT_L(0); PG8_BAR; PG8_MMA(1, 0, At, B0); PG8_MMA(1, 1, At, B1); PG8_BAR; PG8_SCHED;
	s_setprio 0
	s_add_i32 s26, s51, s30
	v_lshl_add_u64 v[144:145], v[144:145], 0, s[8:9]
	s_mov_b32 m0, s26
	ds_read_b128 v[186:189], v152 offset:49152
	ds_read_b128 v[194:197], v152 offset:50176
	ds_read_b128 v[198:201], v152 offset:51200
	ds_read_b128 v[202:205], v152 offset:52224
	ds_read_b128 v[206:209], v152 offset:53248
	ds_read_b128 v[210:213], v152 offset:54272
	ds_read_b128 v[214:217], v152 offset:55296
	ds_read_b128 v[218:221], v152 offset:56320
	global_load_lds_dwordx4 v[144:145], off
	s_add_i32 m0, s26, 0x2000
	s_add_u32 s24, s24, 0x80080
	v_lshl_add_u64 v[144:145], v[190:191], 0, s[8:9]
	s_addc_u32 s25, s25, 0
	s_add_i32 s26, s68, s30
	global_load_lds_dwordx4 v[144:145], off
	v_lshl_add_u64 v[144:145], s[24:25], 0, v[130:131]
	s_mov_b32 m0, s26
	s_nop 0
	global_load_lds_dwordx4 v[144:145], off
	v_lshl_add_u64 v[144:145], s[24:25], 0, v[134:135]
	s_add_i32 m0, s26, 0x2000
	s_nop 0
	global_load_lds_dwordx4 v[144:145], off
	v_lshl_add_u64 v[144:145], v[222:223], 0, s[8:9]
	s_mov_b32 m0, s39
	s_nop 0
	global_load_lds_dwordx4 v[144:145], off
	v_lshl_add_u64 v[144:145], v[224:225], 0, s[8:9]
	s_mov_b32 m0, s40
	s_nop 0
	global_load_lds_dwordx4 v[144:145], off
	s_waitcnt vmcnt(8)
	s_waitcnt lgkmcnt(0)
	s_setprio 1
	s_barrier
	v_mfma_f32_16x16x32_bf16 v[60:63], v[154:157], v[186:189], v[60:63]
	v_mfma_f32_16x16x32_bf16 v[56:59], v[162:165], v[186:189], v[56:59]
	v_mfma_f32_16x16x32_bf16 v[52:55], v[154:157], v[198:201], v[52:55]
	v_mfma_f32_16x16x32_bf16 v[44:47], v[162:165], v[198:201], v[44:47]
	v_mfma_f32_16x16x32_bf16 v[36:39], v[154:157], v[206:209], v[36:39]
	v_mfma_f32_16x16x32_bf16 v[28:31], v[162:165], v[206:209], v[28:31]
	v_mfma_f32_16x16x32_bf16 v[20:23], v[154:157], v[214:217], v[20:23]
	v_mfma_f32_16x16x32_bf16 v[12:15], v[162:165], v[214:217], v[12:15]
	v_mfma_f32_16x16x32_bf16 v[60:63], v[158:161], v[194:197], v[60:63]
	v_mfma_f32_16x16x32_bf16 v[56:59], v[166:169], v[194:197], v[56:59]
	v_mfma_f32_16x16x32_bf16 v[52:55], v[158:161], v[202:205], v[52:55]
	v_mfma_f32_16x16x32_bf16 v[44:47], v[166:169], v[202:205], v[44:47]
	v_mfma_f32_16x16x32_bf16 v[36:39], v[158:161], v[210:213], v[36:39]
	v_mfma_f32_16x16x32_bf16 v[28:31], v[166:169], v[210:213], v[28:31]
	v_mfma_f32_16x16x32_bf16 v[20:23], v[158:161], v[218:221], v[20:23]
	v_mfma_f32_16x16x32_bf16 v[12:15], v[166:169], v[218:221], v[12:15]
	v_mfma_f32_16x16x32_bf16 v[48:51], v[170:173], v[186:189], v[48:51]
	v_mfma_f32_16x16x32_bf16 v[40:43], v[178:181], v[186:189], v[40:43]
	v_mfma_f32_16x16x32_bf16 v[32:35], v[170:173], v[198:201], v[32:35]
	v_mfma_f32_16x16x32_bf16 v[24:27], v[178:181], v[198:201], v[24:27]
	v_mfma_f32_16x16x32_bf16 v[16:19], v[170:173], v[206:209], v[16:19]
	v_mfma_f32_16x16x32_bf16 v[8:11], v[178:181], v[206:209], v[8:11]
	v_mfma_f32_16x16x32_bf16 v[4:7], v[170:173], v[214:217], v[4:7]
	v_mfma_f32_16x16x32_bf16 v[0:3], v[178:181], v[214:217], v[0:3]
	v_mfma_f32_16x16x32_bf16 v[48:51], v[174:177], v[194:197], v[48:51]
	v_mfma_f32_16x16x32_bf16 v[40:43], v[182:185], v[194:197], v[40:43]
	v_mfma_f32_16x16x32_bf16 v[32:35], v[174:177], v[202:205], v[32:35]
	v_mfma_f32_16x16x32_bf16 v[24:27], v[182:185], v[202:205], v[24:27]
	v_mfma_f32_16x16x32_bf16 v[16:19], v[174:177], v[210:213], v[16:19]
	v_mfma_f32_16x16x32_bf16 v[8:11], v[182:185], v[210:213], v[8:11]
	v_mfma_f32_16x16x32_bf16 v[4:7], v[174:177], v[218:221], v[4:7]
	v_mfma_f32_16x16x32_bf16 v[0:3], v[182:185], v[218:221], v[0:3]
	s_barrier
	s_setprio 0
	s_add_i32 s50, s50, 2
	s_add_u32 s22, s22, 0x100
	s_addc_u32 s23, s23, 0
	s_add_u32 s48, s48, 0x100
	s_addc_u32 s49, s49, 0
	s_cmp_gt_u32 s50, 29
	s_cbranch_scc0 .LBB0_216
	s_and_b64 vcc, exec, s[10:11]
	s_cbranch_vccz .LBB0_219
	s_barrier

; #define PG8_STAGE(bufoff, gbase, voff) do { _Pragma("unroll") for (int _i = 0; _i < 2; ++_i) \
;         __builtin_amdgcn_global_load_lds((const unsigned*)((const char*)(gbase) + (voff)[_i]), (LAS unsigned*)(lds + (bufoff) + ldsw + _i * 8192), 16, 0, 0); } while (0)
; #define PG8_LDA(dst, b, h) do { _Pragma("unroll") for (int m = 0; m < 4; ++m) _Pragma("unroll") for (int k = 0; k < 2; ++k) dst[m][k] = *(const LAS bf16x8*)(lds + PG8_SA(b, h) + aoff + m * 2048 + k * 1024); } while (0)
; #define PG8_LDB(dst, b, h) do { _Pragma("unroll") for (int n = 0; n < 2; ++n) _Pragma("unroll") for (int k = 0; k < 2; ++k) dst[n][k] = *(const LAS bf16x8*)(lds + PG8_SB(b, h) + boff + n * 2048 + k * 1024); } while (0)
; #define PG8_MMA(ai, bj, At, Bt) do { __builtin_amdgcn_s_setprio(1); _Pragma("unroll") for (int m = 0; m < 4; ++m) _Pragma("unroll") for (int n = 0; n < 2; ++n) _Pragma("unroll") for (int k = 0; k < 2; ++k) \
;         acc[ai][bj][m][n] = __builtin_amdgcn_mfma_f32_16x16x32_bf16(Bt[n][k], At[m][k], acc[ai][bj][m][n], 0, 0, 0); __builtin_amdgcn_s_setprio(0); } while (0)
; #define PG8_WAIT_V(n) asm volatile("s_waitcnt vmcnt(" #n ")" ::: "memory")
; #define PG8_WAIT_L(n) asm volatile("s_waitcnt lgkmcnt(" #n ")" ::: "memory")
; #define PG8_BAR __builtin_amdgcn_s_barrier()
; template <class Epi, class Sched = StaticOrder, class EpiSub = NoSub, bool FAST = false>
; __device__ __forceinline__ void gemm_phase(LAS unsigned char* lds, const Gemm g, const Sched& S, const Epi& E, const EpiSub& ES = EpiSub()) {
;     ...
;             const bool last = (t == nt - 2);
;             const char* a1 = cA + (size_t)(t + 1) * kstep;
;             const char* a2 = last ? nA : cA + (size_t)(t + 2) * kstep; const char* b2 = last ? nB : cB + (size_t)(t + 2) * kstep;
;             const char* a3 = a2 + kstep; const char* b3 = b2 + kstep;
;             if constexpr (FAST && PG8_SP2) {
;             PG8_LDB(B0, 0, 0); PG8_LDB(B1, 0, 1); PG8_SCHED; PG8_LDA(At, 0, 0); PG8_STAGE(PG8_SA(1, 1), a1 + hstepA, voffA);
;             PG8_WAIT_V(8); PG8_WAIT_L(0); PG8_BAR; PG8_MMA(0, 0, At, B0); PG8_MMA(0, 1, At, B1); PG8_BAR; PG8_SCHED;
;             PG8_LDA(At, 0, 1); PG8_STAGE(PG8_SB(0, 0), b2, voffB); PG8_STAGE(PG8_SB(0, 1), b2 + hstepB, voffB); PG8_STAGE(PG8_SA(0, 0), a2, voffA);
;             PG8_WAIT_V(8); PG8_WAIT_L(0); PG8_BAR; PG8_MMA(1, 0, At, B0); PG8_MMA(1, 1, At, B1); PG8_BAR; PG8_SCHED;
.LBB0_600:
	ds_read_b128 v[100:103], v186
	ds_read_b128 v[112:115], v186 offset:1024
	ds_read_b128 v[124:127], v186 offset:2048
	ds_read_b128 v[136:139], v186 offset:3072
	ds_read_b128 v[144:147], v187
	ds_read_b128 v[148:151], v187 offset:1024
	ds_read_b128 v[152:155], v187 offset:2048
	ds_read_b128 v[170:173], v187 offset:3072
	s_add_i32 s51, s50, 2
	s_add_u32 s42, s40, 0xfffc0080
	s_addc_u32 s43, s41, -1
	s_cmp_eq_u32 s33, s50
	s_cselect_b32 s53, s1, s43
	s_cselect_b32 s52, s5, s42
	s_cselect_b32 s43, s7, s49
	s_cselect_b32 s42, s25, s48
	v_lshl_add_u64 v[190:191], s[40:41], 0, v[164:165]
	s_add_i32 m0, s55, 0xc000
	ds_read_b128 v[174:177], v188
	ds_read_b128 v[178:181], v188 offset:1024
	ds_read_b128 v[194:197], v188 offset:2048
	ds_read_b128 v[198:201], v188 offset:3072
	ds_read_b128 v[202:205], v188 offset:4096
	ds_read_b128 v[206:209], v188 offset:5120
	ds_read_b128 v[210:213], v188 offset:6144
	ds_read_b128 v[214:217], v188 offset:7168
	global_load_lds_dwordx4 v[190:191], off
	v_lshl_add_u64 v[190:191], s[40:41], 0, v[166:167]
	s_add_i32 m0, s55, 0xe000
	s_nop 0
	global_load_lds_dwordx4 v[190:191], off
	s_waitcnt vmcnt(8)
	s_waitcnt lgkmcnt(0)
	s_setprio 1
	s_barrier
	v_mfma_f32_16x16x32_bf16 v[140:143], v[100:103], v[174:177], v[140:143]
	v_mfma_f32_16x16x32_bf16 v[132:135], v[124:127], v[174:177], v[132:135]
	v_mfma_f32_16x16x32_bf16 v[116:119], v[100:103], v[194:197], v[116:119]
	v_mfma_f32_16x16x32_bf16 v[108:111], v[124:127], v[194:197], v[108:111]
	v_mfma_f32_16x16x32_bf16 v[92:95], v[100:103], v[202:205], v[92:95]
	v_mfma_f32_16x16x32_bf16 v[88:91], v[124:127], v[202:205], v[88:91]
	v_mfma_f32_16x16x32_bf16 v[76:79], v[100:103], v[210:213], v[76:79]
	v_mfma_f32_16x16x32_bf16 v[72:75], v[124:127], v[210:213], v[72:75]
	v_mfma_f32_16x16x32_bf16 v[140:143], v[112:115], v[178:181], v[140:143]
	v_mfma_f32_16x16x32_bf16 v[132:135], v[136:139], v[178:181], v[132:135]
	v_mfma_f32_16x16x32_bf16 v[116:119], v[112:115], v[198:201], v[116:119]
	v_mfma_f32_16x16x32_bf16 v[108:111], v[136:139], v[198:201], v[108:111]
	v_mfma_f32_16x16x32_bf16 v[92:95], v[112:115], v[206:209], v[92:95]
	v_mfma_f32_16x16x32_bf16 v[88:91], v[136:139], v[206:209], v[88:91]
	v_mfma_f32_16x16x32_bf16 v[76:79], v[112:115], v[214:217], v[76:79]
	v_mfma_f32_16x16x32_bf16 v[72:75], v[136:139], v[214:217], v[72:75]
	v_mfma_f32_16x16x32_bf16 v[128:131], v[144:147], v[174:177], v[128:131]
	v_mfma_f32_16x16x32_bf16 v[120:123], v[152:155], v[174:177], v[120:123]
	v_mfma_f32_16x16x32_bf16 v[104:107], v[144:147], v[194:197], v[104:107]
	v_mfma_f32_16x16x32_bf16 v[96:99], v[152:155], v[194:197], v[96:99]
	v_mfma_f32_16x16x32_bf16 v[84:87], v[144:147], v[202:205], v[84:87]
	v_mfma_f32_16x16x32_bf16 v[80:83], v[152:155], v[202:205], v[80:83]
	v_mfma_f32_16x16x32_bf16 v[68:71], v[144:147], v[210:213], v[68:71]
	v_mfma_f32_16x16x32_bf16 v[64:67], v[152:155], v[210:213], v[64:67]
	v_mfma_f32_16x16x32_bf16 v[128:131], v[148:151], v[178:181], v[128:131]
	v_mfma_f32_16x16x32_bf16 v[120:123], v[170:173], v[178:181], v[120:123]
	v_mfma_f32_16x16x32_bf16 v[104:107], v[148:151], v[198:201], v[104:107]
	v_mfma_f32_16x16x32_bf16 v[96:99], v[170:173], v[198:201], v[96:99]
	v_mfma_f32_16x16x32_bf16 v[84:87], v[148:151], v[206:209], v[84:87]
	v_mfma_f32_16x16x32_bf16 v[80:83], v[170:173], v[206:209], v[80:83]
	v_mfma_f32_16x16x32_bf16 v[68:71], v[148:151], v[214:217], v[68:71]
	v_mfma_f32_16x16x32_bf16 v[64:67], v[170:173], v[214:217], v[64:67]
	s_barrier
	s_setprio 0
	s_add_i32 s50, s75, s54
	v_lshl_add_u64 v[190:191], s[42:43], 0, v[158:159]
	s_mov_b32 m0, s50
	ds_read_b128 v[174:177], v188 offset:16384
	ds_read_b128 v[178:181], v188 offset:17408
	ds_read_b128 v[194:197], v188 offset:18432
	ds_read_b128 v[198:201], v188 offset:19456
	ds_read_b128 v[202:205], v188 offset:20480
	ds_read_b128 v[206:209], v188 offset:21504
	ds_read_b128 v[210:213], v188 offset:22528
	ds_read_b128 v[214:217], v188 offset:23552
	global_load_lds_dwordx4 v[190:191], off
	s_add_i32 m0, s50, 0x2000
	s_add_u32 s70, s42, 0x40000
	v_lshl_add_u64 v[218:219], s[42:43], 0, v[162:163]
	s_addc_u32 s71, s43, 0
	s_add_i32 s50, s80, s54
	global_load_lds_dwordx4 v[218:219], off
	v_lshl_add_u64 v[220:221], s[70:71], 0, v[158:159]
	s_mov_b32 m0, s50
	v_lshl_add_u64 v[222:223], s[52:53], 0, v[160:161]
	global_load_lds_dwordx4 v[220:221], off
	v_lshl_add_u64 v[220:221], s[70:71], 0, v[162:163]
	s_add_i32 m0, s50, 0x2000
	s_nop 0
	global_load_lds_dwordx4 v[220:221], off
	v_lshl_add_u64 v[220:221], s[52:53], 0, v[156:157]
	s_mov_b32 m0, s55
	s_nop 0
	global_load_lds_dwordx4 v[220:221], off
	s_mov_b32 m0, s56
	s_nop 0
	global_load_lds_dwordx4 v[222:223], off
	s_waitcnt vmcnt(8)
	s_waitcnt lgkmcnt(0)
	s_setprio 1
	s_barrier
; #define PG8_STAGE(bufoff, gbase, voff) do { _Pragma("unroll") for (int _i = 0; _i < 2; ++_i) \
;         __builtin_amdgcn_global_load_lds((const unsigned*)((const char*)(gbase) + (voff)[_i]), (LAS unsigned*)(lds + (bufoff) + ldsw + _i * 8192), 16, 0, 0); } while (0)
; #define PG8_LDA(dst, b, h) do { _Pragma("unroll") for (int m = 0; m < 4; ++m) _Pragma("unroll") for (int k = 0; k < 2; ++k) dst[m][k] = *(const LAS bf16x8*)(lds + PG8_SA(b, h) + aoff + m * 2048 + k * 1024); } while (0)
; #define PG8_LDB(dst, b, h) do { _Pragma("unroll") for (int n = 0; n < 2; ++n) _Pragma("unroll") for (int k = 0; k < 2; ++k) dst[n][k] = *(const LAS bf16x8*)(lds + PG8_SB(b, h) + boff + n * 2048 + k * 1024); } while (0)
; #define PG8_MMA(ai, bj, At, Bt) do { __builtin_amdgcn_s_setprio(1); _Pragma("unroll") for (int m = 0; m < 4; ++m) _Pragma("unroll") for (int n = 0; n < 2; ++n) _Pragma("unroll") for (int k = 0; k < 2; ++k) \
;         acc[ai][bj][m][n] = __builtin_amdgcn_mfma_f32_16x16x32_bf16(Bt[n][k], At[m][k], acc[ai][bj][m][n], 0, 0, 0); __builtin_amdgcn_s_setprio(0); } while (0)
; #define PG8_WAIT_V(n) asm volatile("s_waitcnt vmcnt(" #n ")" ::: "memory")
; #define PG8_WAIT_L(n) asm volatile("s_waitcnt lgkmcnt(" #n ")" ::: "memory")
; #define PG8_BAR __builtin_amdgcn_s_barrier()
; #define PG8_SCHED __builtin_amdgcn_sched_barrier(0)
; template <class Epi, class Sched = StaticOrder, class EpiSub = NoSub, bool FAST = false>
; __device__ __forceinline__ void gemm_phase(LAS unsigned char* lds, const Gemm g, const Sched& S, const Epi& E, const EpiSub& ES = EpiSub()) {
;     ...
;             PG8_WAIT_V(8); PG8_WAIT_L(0); PG8_BAR; PG8_MMA(1, 0, At, B0); PG8_MMA(1, 1, At, B1); PG8_BAR; PG8_SCHED;
;             PG8_LDB(B0, 1, 0); PG8_LDB(B1, 1, 1); PG8_SCHED; PG8_LDA(At, 1, 0); PG8_STAGE(PG8_SA(0, 1), a2 + hstepA, voffA);
;             PG8_WAIT_V(8); PG8_WAIT_L(0); PG8_BAR; PG8_MMA(0, 0, At, B0); PG8_MMA(0, 1, At, B1); PG8_BAR; PG8_SCHED;
	v_mfma_f32_16x16x32_bf16 v[60:63], v[100:103], v[174:177], v[60:63]
	v_mfma_f32_16x16x32_bf16 v[56:59], v[124:127], v[174:177], v[56:59]
	v_mfma_f32_16x16x32_bf16 v[44:47], v[100:103], v[194:197], v[44:47]
	v_mfma_f32_16x16x32_bf16 v[40:43], v[124:127], v[194:197], v[40:43]
	v_mfma_f32_16x16x32_bf16 v[28:31], v[100:103], v[202:205], v[28:31]
	v_mfma_f32_16x16x32_bf16 v[24:27], v[124:127], v[202:205], v[24:27]
	v_mfma_f32_16x16x32_bf16 v[12:15], v[100:103], v[210:213], v[12:15]
	v_mfma_f32_16x16x32_bf16 v[8:11], v[124:127], v[210:213], v[8:11]
	v_mfma_f32_16x16x32_bf16 v[60:63], v[112:115], v[178:181], v[60:63]
	v_mfma_f32_16x16x32_bf16 v[56:59], v[136:139], v[178:181], v[56:59]
	v_mfma_f32_16x16x32_bf16 v[44:47], v[112:115], v[198:201], v[44:47]
	v_mfma_f32_16x16x32_bf16 v[40:43], v[136:139], v[198:201], v[40:43]
	v_mfma_f32_16x16x32_bf16 v[28:31], v[112:115], v[206:209], v[28:31]
	v_mfma_f32_16x16x32_bf16 v[24:27], v[136:139], v[206:209], v[24:27]
	v_mfma_f32_16x16x32_bf16 v[12:15], v[112:115], v[214:217], v[12:15]
	v_mfma_f32_16x16x32_bf16 v[8:11], v[136:139], v[214:217], v[8:11]
	v_mfma_f32_16x16x32_bf16 v[52:55], v[144:147], v[174:177], v[52:55]
	v_mfma_f32_16x16x32_bf16 v[48:51], v[152:155], v[174:177], v[48:51]
	v_mfma_f32_16x16x32_bf16 v[36:39], v[144:147], v[194:197], v[36:39]
	v_mfma_f32_16x16x32_bf16 v[32:35], v[152:155], v[194:197], v[32:35]
	v_mfma_f32_16x16x32_bf16 v[20:23], v[144:147], v[202:205], v[20:23]
	v_mfma_f32_16x16x32_bf16 v[16:19], v[152:155], v[202:205], v[16:19]
	v_mfma_f32_16x16x32_bf16 v[4:7], v[144:147], v[210:213], v[4:7]
	v_mfma_f32_16x16x32_bf16 v[0:3], v[152:155], v[210:213], v[0:3]
	v_mfma_f32_16x16x32_bf16 v[52:55], v[148:151], v[178:181], v[52:55]
	v_mfma_f32_16x16x32_bf16 v[48:51], v[170:173], v[178:181], v[48:51]
	v_mfma_f32_16x16x32_bf16 v[36:39], v[148:151], v[198:201], v[36:39]
	v_mfma_f32_16x16x32_bf16 v[32:35], v[170:173], v[198:201], v[32:35]
	v_mfma_f32_16x16x32_bf16 v[20:23], v[148:151], v[206:209], v[20:23]
	v_mfma_f32_16x16x32_bf16 v[16:19], v[170:173], v[206:209], v[16:19]
	v_mfma_f32_16x16x32_bf16 v[4:7], v[148:151], v[214:217], v[4:7]
	v_mfma_f32_16x16x32_bf16 v[0:3], v[170:173], v[214:217], v[0:3]
	s_barrier
	s_setprio 0
	s_add_i32 s50, 0, 0x18000
	s_add_i32 s70, 0, 0x1c000
	v_add_u32_e32 v136, s50, v183
	v_add_u32_e32 v170, s70, v183
	ds_read_b128 v[100:103], v136
	ds_read_b128 v[112:115], v136 offset:1024
	ds_read_b128 v[124:127], v136 offset:2048
	ds_read_b128 v[136:139], v136 offset:3072
	ds_read_b128 v[144:147], v170
	ds_read_b128 v[148:151], v170 offset:1024
	ds_read_b128 v[152:155], v170 offset:2048
	ds_read_b128 v[170:173], v170 offset:3072
	s_add_u32 s52, s52, 0x40000
	s_addc_u32 s53, s53, 0
	s_mov_b32 m0, s57
	v_lshl_add_u64 v[224:225], s[52:53], 0, v[156:157]
	ds_read_b128 v[174:177], v188 offset:32768
	ds_read_b128 v[178:181], v188 offset:33792
	ds_read_b128 v[194:197], v188 offset:34816
	ds_read_b128 v[198:201], v188 offset:35840
	ds_read_b128 v[202:205], v188 offset:36864
	ds_read_b128 v[206:209], v188 offset:37888
	ds_read_b128 v[210:213], v188 offset:38912
	ds_read_b128 v[214:217], v188 offset:39936
	global_load_lds_dwordx4 v[224:225], off
	v_lshl_add_u64 v[224:225], s[52:53], 0, v[160:161]
	s_mov_b32 m0, s58
	s_nop 0
	global_load_lds_dwordx4 v[224:225], off
	s_waitcnt vmcnt(8)
	s_waitcnt lgkmcnt(0)
	s_setprio 1
	s_barrier
	v_mfma_f32_16x16x32_bf16 v[140:143], v[100:103], v[174:177], v[140:143]
	v_mfma_f32_16x16x32_bf16 v[132:135], v[124:127], v[174:177], v[132:135]
	v_mfma_f32_16x16x32_bf16 v[116:119], v[100:103], v[194:197], v[116:119]
	v_mfma_f32_16x16x32_bf16 v[108:111], v[124:127], v[194:197], v[108:111]
	v_mfma_f32_16x16x32_bf16 v[92:95], v[100:103], v[202:205], v[92:95]
	v_mfma_f32_16x16x32_bf16 v[88:91], v[124:127], v[202:205], v[88:91]
	v_mfma_f32_16x16x32_bf16 v[76:79], v[100:103], v[210:213], v[76:79]
	v_mfma_f32_16x16x32_bf16 v[72:75], v[124:127], v[210:213], v[72:75]
	v_mfma_f32_16x16x32_bf16 v[140:143], v[112:115], v[178:181], v[140:143]
	v_mfma_f32_16x16x32_bf16 v[132:135], v[136:139], v[178:181], v[132:135]
	v_mfma_f32_16x16x32_bf16 v[116:119], v[112:115], v[198:201], v[116:119]
	v_mfma_f32_16x16x32_bf16 v[108:111], v[136:139], v[198:201], v[108:111]
	v_mfma_f32_16x16x32_bf16 v[92:95], v[112:115], v[206:209], v[92:95]
	v_mfma_f32_16x16x32_bf16 v[88:91], v[136:139], v[206:209], v[88:91]
	v_mfma_f32_16x16x32_bf16 v[76:79], v[112:115], v[214:217], v[76:79]
	v_mfma_f32_16x16x32_bf16 v[72:75], v[136:139], v[214:217], v[72:75]
	v_mfma_f32_16x16x32_bf16 v[128:131], v[144:147], v[174:177], v[128:131]
	v_mfma_f32_16x16x32_bf16 v[120:123], v[152:155], v[174:177], v[120:123]
	v_mfma_f32_16x16x32_bf16 v[104:107], v[144:147], v[194:197], v[104:107]
	v_mfma_f32_16x16x32_bf16 v[96:99], v[152:155], v[194:197], v[96:99]
	v_mfma_f32_16x16x32_bf16 v[84:87], v[144:147], v[202:205], v[84:87]
	v_mfma_f32_16x16x32_bf16 v[80:83], v[152:155], v[202:205], v[80:83]
	v_mfma_f32_16x16x32_bf16 v[68:71], v[144:147], v[210:213], v[68:71]
	v_mfma_f32_16x16x32_bf16 v[64:67], v[152:155], v[210:213], v[64:67]
	v_mfma_f32_16x16x32_bf16 v[128:131], v[148:151], v[178:181], v[128:131]
	v_mfma_f32_16x16x32_bf16 v[120:123], v[170:173], v[178:181], v[120:123]
	v_mfma_f32_16x16x32_bf16 v[104:107], v[148:151], v[198:201], v[104:107]
	v_mfma_f32_16x16x32_bf16 v[96:99], v[170:173], v[198:201], v[96:99]
	v_mfma_f32_16x16x32_bf16 v[84:87], v[148:151], v[206:209], v[84:87]
	v_mfma_f32_16x16x32_bf16 v[80:83], v[170:173], v[206:209], v[80:83]
	v_mfma_f32_16x16x32_bf16 v[68:71], v[148:151], v[214:217], v[68:71]
	v_mfma_f32_16x16x32_bf16 v[64:67], v[170:173], v[214:217], v[64:67]
	s_barrier
; #define PG8_STAGE(bufoff, gbase, voff) do { _Pragma("unroll") for (int _i = 0; _i < 2; ++_i) \
;         __builtin_amdgcn_global_load_lds((const unsigned*)((const char*)(gbase) + (voff)[_i]), (LAS unsigned*)(lds + (bufoff) + ldsw + _i * 8192), 16, 0, 0); } while (0)
; #define PG8_LDA(dst, b, h) do { _Pragma("unroll") for (int m = 0; m < 4; ++m) _Pragma("unroll") for (int k = 0; k < 2; ++k) dst[m][k] = *(const LAS bf16x8*)(lds + PG8_SA(b, h) + aoff + m * 2048 + k * 1024); } while (0)
; #define PG8_MMA(ai, bj, At, Bt) do { __builtin_amdgcn_s_setprio(1); _Pragma("unroll") for (int m = 0; m < 4; ++m) _Pragma("unroll") for (int n = 0; n < 2; ++n) _Pragma("unroll") for (int k = 0; k < 2; ++k) \
;         acc[ai][bj][m][n] = __builtin_amdgcn_mfma_f32_16x16x32_bf16(Bt[n][k], At[m][k], acc[ai][bj][m][n], 0, 0, 0); __builtin_amdgcn_s_setprio(0); } while (0)
; #define PG8_WAIT_V(n) asm volatile("s_waitcnt vmcnt(" #n ")" ::: "memory")
; #define PG8_WAIT_L(n) asm volatile("s_waitcnt lgkmcnt(" #n ")" ::: "memory")
; #define PG8_BAR __builtin_amdgcn_s_barrier()
; #define PG8_SCHED __builtin_amdgcn_sched_barrier(0)
; template <class Epi, class Sched = StaticOrder, class EpiSub = NoSub, bool FAST = false>
; __device__ __forceinline__ void gemm_phase(LAS unsigned char* lds, const Gemm g, const Sched& S, const Epi& E, const EpiSub& ES = EpiSub()) {
;     ...
;         for (int t = 0; t < nt; t += 2) {
;     ...
;             PG8_LDA(At, 1, 1); PG8_STAGE(PG8_SB(1, 0), b3, voffB); PG8_STAGE(PG8_SB(1, 1), b3 + hstepB, voffB); PG8_STAGE(PG8_SA(1, 0), a3, voffA);
;             PG8_WAIT_V(8); PG8_WAIT_L(0); PG8_BAR; PG8_MMA(1, 0, At, B0); PG8_MMA(1, 1, At, B1); PG8_BAR; PG8_SCHED;
	s_setprio 0
	s_add_i32 s50, s50, s54
	v_lshl_add_u64 v[190:191], v[190:191], 0, s[12:13]
	s_mov_b32 m0, s50
	ds_read_b128 v[174:177], v188 offset:49152
	ds_read_b128 v[178:181], v188 offset:50176
	ds_read_b128 v[194:197], v188 offset:51200
	ds_read_b128 v[198:201], v188 offset:52224
	ds_read_b128 v[202:205], v188 offset:53248
	ds_read_b128 v[206:209], v188 offset:54272
	ds_read_b128 v[210:213], v188 offset:55296
	ds_read_b128 v[214:217], v188 offset:56320
	global_load_lds_dwordx4 v[190:191], off
	s_add_i32 m0, s50, 0x2000
	s_add_u32 s42, s42, 0x40080
	v_lshl_add_u64 v[190:191], v[218:219], 0, s[12:13]
	s_addc_u32 s43, s43, 0
	s_add_i32 s50, s70, s54
	global_load_lds_dwordx4 v[190:191], off
	v_lshl_add_u64 v[190:191], s[42:43], 0, v[158:159]
	s_mov_b32 m0, s50
	s_nop 0
	global_load_lds_dwordx4 v[190:191], off
	v_lshl_add_u64 v[190:191], s[42:43], 0, v[162:163]
	s_add_i32 m0, s50, 0x2000
	s_nop 0
	global_load_lds_dwordx4 v[190:191], off
	v_lshl_add_u64 v[190:191], v[220:221], 0, s[12:13]
	s_mov_b32 m0, s69
	s_nop 0
	global_load_lds_dwordx4 v[190:191], off
	v_lshl_add_u64 v[190:191], v[222:223], 0, s[12:13]
	s_mov_b32 m0, s74
	s_nop 0
	global_load_lds_dwordx4 v[190:191], off
	s_waitcnt vmcnt(8)
	s_waitcnt lgkmcnt(0)
	s_setprio 1
	s_barrier
	v_mfma_f32_16x16x32_bf16 v[60:63], v[100:103], v[174:177], v[60:63]
	v_mfma_f32_16x16x32_bf16 v[56:59], v[124:127], v[174:177], v[56:59]
	v_mfma_f32_16x16x32_bf16 v[44:47], v[100:103], v[194:197], v[44:47]
	v_mfma_f32_16x16x32_bf16 v[40:43], v[124:127], v[194:197], v[40:43]
	v_mfma_f32_16x16x32_bf16 v[28:31], v[100:103], v[202:205], v[28:31]
	v_mfma_f32_16x16x32_bf16 v[24:27], v[124:127], v[202:205], v[24:27]
	v_mfma_f32_16x16x32_bf16 v[12:15], v[100:103], v[210:213], v[12:15]
	v_mfma_f32_16x16x32_bf16 v[8:11], v[124:127], v[210:213], v[8:11]
	v_mfma_f32_16x16x32_bf16 v[60:63], v[112:115], v[178:181], v[60:63]
	v_mfma_f32_16x16x32_bf16 v[56:59], v[136:139], v[178:181], v[56:59]
	v_mfma_f32_16x16x32_bf16 v[44:47], v[112:115], v[198:201], v[44:47]
	v_mfma_f32_16x16x32_bf16 v[40:43], v[136:139], v[198:201], v[40:43]
	v_mfma_f32_16x16x32_bf16 v[28:31], v[112:115], v[206:209], v[28:31]
	v_mfma_f32_16x16x32_bf16 v[24:27], v[136:139], v[206:209], v[24:27]
	v_mfma_f32_16x16x32_bf16 v[12:15], v[112:115], v[214:217], v[12:15]
	v_mfma_f32_16x16x32_bf16 v[8:11], v[136:139], v[214:217], v[8:11]
	v_mfma_f32_16x16x32_bf16 v[52:55], v[144:147], v[174:177], v[52:55]
	v_mfma_f32_16x16x32_bf16 v[48:51], v[152:155], v[174:177], v[48:51]
	v_mfma_f32_16x16x32_bf16 v[36:39], v[144:147], v[194:197], v[36:39]
	v_mfma_f32_16x16x32_bf16 v[32:35], v[152:155], v[194:197], v[32:35]
	v_mfma_f32_16x16x32_bf16 v[20:23], v[144:147], v[202:205], v[20:23]
	v_mfma_f32_16x16x32_bf16 v[16:19], v[152:155], v[202:205], v[16:19]
	v_mfma_f32_16x16x32_bf16 v[4:7], v[144:147], v[210:213], v[4:7]
	v_mfma_f32_16x16x32_bf16 v[0:3], v[152:155], v[210:213], v[0:3]
	v_mfma_f32_16x16x32_bf16 v[52:55], v[148:151], v[178:181], v[52:55]
	v_mfma_f32_16x16x32_bf16 v[48:51], v[170:173], v[178:181], v[48:51]
	v_mfma_f32_16x16x32_bf16 v[36:39], v[148:151], v[198:201], v[36:39]
	v_mfma_f32_16x16x32_bf16 v[32:35], v[170:173], v[198:201], v[32:35]
	v_mfma_f32_16x16x32_bf16 v[20:23], v[148:151], v[206:209], v[20:23]
	v_mfma_f32_16x16x32_bf16 v[16:19], v[170:173], v[206:209], v[16:19]
	v_mfma_f32_16x16x32_bf16 v[4:7], v[148:151], v[214:217], v[4:7]
	v_mfma_f32_16x16x32_bf16 v[0:3], v[170:173], v[214:217], v[0:3]
	s_barrier
	s_setprio 0
	s_add_u32 s40, s40, 0x100
	s_addc_u32 s41, s41, 0
	s_add_u32 s48, s48, 0x100
	s_addc_u32 s49, s49, 0
	s_cmp_ge_u32 s51, s27
	s_mov_b32 s50, s51
	s_cbranch_scc0 .LBB0_600
	s_and_b64 vcc, exec, s[14:15]
	s_cbranch_vccz .LBB0_603
	s_barrier

; #define PG8_STAGE(bufoff, gbase, voff) do { _Pragma("unroll") for (int _i = 0; _i < 2; ++_i) \
;         __builtin_amdgcn_global_load_lds((const unsigned*)((const char*)(gbase) + (voff)[_i]), (LAS unsigned*)(lds + (bufoff) + ldsw + _i * 8192), 16, 0, 0); } while (0)
; #define PG8_LDA(dst, b, h) do { _Pragma("unroll") for (int m = 0; m < 4; ++m) _Pragma("unroll") for (int k = 0; k < 2; ++k) dst[m][k] = *(const LAS bf16x8*)(lds + PG8_SA(b, h) + aoff + m * 2048 + k * 1024); } while (0)
; #define PG8_LDB(dst, b, h) do { _Pragma("unroll") for (int n = 0; n < 2; ++n) _Pragma("unroll") for (int k = 0; k < 2; ++k) dst[n][k] = *(const LAS bf16x8*)(lds + PG8_SB(b, h) + boff + n * 2048 + k * 1024); } while (0)
; #define PG8_MMA(ai, bj, At, Bt) do { __builtin_amdgcn_s_setprio(1); _Pragma("unroll") for (int m = 0; m < 4; ++m) _Pragma("unroll") for (int n = 0; n < 2; ++n) _Pragma("unroll") for (int k = 0; k < 2; ++k) \
;         acc[ai][bj][m][n] = __builtin_amdgcn_mfma_f32_16x16x32_bf16(Bt[n][k], At[m][k], acc[ai][bj][m][n], 0, 0, 0); __builtin_amdgcn_s_setprio(0); } while (0)
; #define PG8_WAIT_V(n) asm volatile("s_waitcnt vmcnt(" #n ")" ::: "memory")
; #define PG8_WAIT_L(n) asm volatile("s_waitcnt lgkmcnt(" #n ")" ::: "memory")
; #define PG8_BAR __builtin_amdgcn_s_barrier()
; template <class Epi, class Sched = StaticOrder, class EpiSub = NoSub, bool FAST = false>
; __device__ __forceinline__ void gemm_phase(LAS unsigned char* lds, const Gemm g, const Sched& S, const Epi& E, const EpiSub& ES = EpiSub()) {
;     ...
;             const bool last = (t == nt - 2);
;             const char* a1 = cA + (size_t)(t + 1) * kstep;
;             const char* a2 = last ? nA : cA + (size_t)(t + 2) * kstep; const char* b2 = last ? nB : cB + (size_t)(t + 2) * kstep;
;             const char* a3 = a2 + kstep; const char* b3 = b2 + kstep;
;             if constexpr (FAST && PG8_SP2) {
;             PG8_LDB(B0, 0, 0); PG8_LDB(B1, 0, 1); PG8_SCHED; PG8_LDA(At, 0, 0); PG8_STAGE(PG8_SA(1, 1), a1 + hstepA, voffA);
;             PG8_WAIT_V(8); PG8_WAIT_L(0); PG8_BAR; PG8_MMA(0, 0, At, B0); PG8_MMA(0, 1, At, B1); PG8_BAR; PG8_SCHED;
;             PG8_LDA(At, 0, 1); PG8_STAGE(PG8_SB(0, 0), b2, voffB); PG8_STAGE(PG8_SB(0, 1), b2 + hstepB, voffB); PG8_STAGE(PG8_SA(0, 0), a2, voffA);
;             PG8_WAIT_V(8); PG8_WAIT_L(0); PG8_BAR; PG8_MMA(1, 0, At, B0); PG8_MMA(1, 1, At, B1); PG8_BAR; PG8_SCHED;
.LBB0_632:
	ds_read_b128 v[104:107], v224
	ds_read_b128 v[108:111], v224 offset:1024
	ds_read_b128 v[120:123], v224 offset:2048
	ds_read_b128 v[124:127], v224 offset:3072
	ds_read_b128 v[136:139], v225
	ds_read_b128 v[140:143], v225 offset:1024
	ds_read_b128 v[152:155], v225 offset:2048
	ds_read_b128 v[156:159], v225 offset:3072
	s_add_i32 s50, s42, 2
	s_add_u32 s40, s38, 0xfff80080
	s_addc_u32 s41, s39, -1
	s_cmp_eq_u32 s33, s42
	s_cselect_b32 s42, s5, s40
	s_cselect_b32 s43, s1, s41
	s_cselect_b32 s41, s21, s49
	s_cselect_b32 s40, s23, s48
	v_lshl_add_u64 v[208:209], s[38:39], 0, v[202:203]
	s_add_i32 m0, s53, 0xc000
	ds_read_b128 v[160:163], v226
	ds_read_b128 v[164:167], v226 offset:1024
	ds_read_b128 v[168:171], v226 offset:2048
	ds_read_b128 v[172:175], v226 offset:3072
	ds_read_b128 v[176:179], v226 offset:4096
	ds_read_b128 v[180:183], v226 offset:5120
	ds_read_b128 v[184:187], v226 offset:6144
	ds_read_b128 v[188:191], v226 offset:7168
	global_load_lds_dwordx4 v[208:209], off
	v_lshl_add_u64 v[208:209], s[38:39], 0, v[204:205]
	s_add_i32 m0, s53, 0xe000
	s_nop 0
	global_load_lds_dwordx4 v[208:209], off
	s_waitcnt vmcnt(8)
	s_waitcnt lgkmcnt(0)
	s_setprio 1
	s_barrier
	v_mfma_f32_16x16x32_bf16 v[148:151], v[104:107], v[160:163], v[148:151]
	v_mfma_f32_16x16x32_bf16 v[144:147], v[120:123], v[160:163], v[144:147]
	v_mfma_f32_16x16x32_bf16 v[116:119], v[104:107], v[168:171], v[116:119]
	v_mfma_f32_16x16x32_bf16 v[112:115], v[120:123], v[168:171], v[112:115]
	v_mfma_f32_16x16x32_bf16 v[92:95], v[104:107], v[176:179], v[92:95]
	v_mfma_f32_16x16x32_bf16 v[88:91], v[120:123], v[176:179], v[88:91]
	v_mfma_f32_16x16x32_bf16 v[76:79], v[104:107], v[184:187], v[76:79]
	v_mfma_f32_16x16x32_bf16 v[72:75], v[120:123], v[184:187], v[72:75]
	v_mfma_f32_16x16x32_bf16 v[148:151], v[108:111], v[164:167], v[148:151]
	v_mfma_f32_16x16x32_bf16 v[144:147], v[124:127], v[164:167], v[144:147]
	v_mfma_f32_16x16x32_bf16 v[116:119], v[108:111], v[172:175], v[116:119]
	v_mfma_f32_16x16x32_bf16 v[112:115], v[124:127], v[172:175], v[112:115]
	v_mfma_f32_16x16x32_bf16 v[92:95], v[108:111], v[180:183], v[92:95]
	v_mfma_f32_16x16x32_bf16 v[88:91], v[124:127], v[180:183], v[88:91]
	v_mfma_f32_16x16x32_bf16 v[76:79], v[108:111], v[188:191], v[76:79]
	v_mfma_f32_16x16x32_bf16 v[72:75], v[124:127], v[188:191], v[72:75]
	v_mfma_f32_16x16x32_bf16 v[132:135], v[136:139], v[160:163], v[132:135]
	v_mfma_f32_16x16x32_bf16 v[128:131], v[152:155], v[160:163], v[128:131]
	v_mfma_f32_16x16x32_bf16 v[100:103], v[136:139], v[168:171], v[100:103]
	v_mfma_f32_16x16x32_bf16 v[96:99], v[152:155], v[168:171], v[96:99]
	v_mfma_f32_16x16x32_bf16 v[84:87], v[136:139], v[176:179], v[84:87]
	v_mfma_f32_16x16x32_bf16 v[80:83], v[152:155], v[176:179], v[80:83]
	v_mfma_f32_16x16x32_bf16 v[68:71], v[136:139], v[184:187], v[68:71]
	v_mfma_f32_16x16x32_bf16 v[64:67], v[152:155], v[184:187], v[64:67]
	v_mfma_f32_16x16x32_bf16 v[132:135], v[140:143], v[164:167], v[132:135]
	v_mfma_f32_16x16x32_bf16 v[128:131], v[156:159], v[164:167], v[128:131]
	v_mfma_f32_16x16x32_bf16 v[100:103], v[140:143], v[172:175], v[100:103]
	v_mfma_f32_16x16x32_bf16 v[96:99], v[156:159], v[172:175], v[96:99]
	v_mfma_f32_16x16x32_bf16 v[84:87], v[140:143], v[180:183], v[84:87]
	v_mfma_f32_16x16x32_bf16 v[80:83], v[156:159], v[180:183], v[80:83]
	v_mfma_f32_16x16x32_bf16 v[68:71], v[140:143], v[188:191], v[68:71]
	v_mfma_f32_16x16x32_bf16 v[64:67], v[156:159], v[188:191], v[64:67]
	s_barrier
	s_setprio 0
	s_add_i32 s51, s75, s52
	v_lshl_add_u64 v[208:209], s[40:41], 0, v[196:197]
	s_mov_b32 m0, s51
	ds_read_b128 v[160:163], v226 offset:16384
	ds_read_b128 v[164:167], v226 offset:17408
	ds_read_b128 v[168:171], v226 offset:18432
	ds_read_b128 v[172:175], v226 offset:19456
	ds_read_b128 v[176:179], v226 offset:20480
	ds_read_b128 v[180:183], v226 offset:21504
	ds_read_b128 v[184:187], v226 offset:22528
	ds_read_b128 v[188:191], v226 offset:23552
	global_load_lds_dwordx4 v[208:209], off
	s_add_i32 m0, s51, 0x2000
	s_add_u32 s70, s40, 0x80000
	v_lshl_add_u64 v[210:211], s[40:41], 0, v[200:201]
	s_addc_u32 s71, s41, 0
	s_add_i32 s51, s78, s52
	global_load_lds_dwordx4 v[210:211], off
	v_lshl_add_u64 v[212:213], s[70:71], 0, v[196:197]
	s_mov_b32 m0, s51
	v_lshl_add_u64 v[214:215], s[42:43], 0, v[198:199]
	global_load_lds_dwordx4 v[212:213], off
	v_lshl_add_u64 v[212:213], s[70:71], 0, v[200:201]
	s_add_i32 m0, s51, 0x2000
	s_nop 0
	global_load_lds_dwordx4 v[212:213], off
	v_lshl_add_u64 v[212:213], s[42:43], 0, v[194:195]
	s_mov_b32 m0, s53
	s_nop 0
	global_load_lds_dwordx4 v[212:213], off
	s_mov_b32 m0, s54
	s_nop 0
	global_load_lds_dwordx4 v[214:215], off
	s_waitcnt vmcnt(8)
	s_waitcnt lgkmcnt(0)
	s_setprio 1
	s_barrier
; #define PG8_STAGE(bufoff, gbase, voff) do { _Pragma("unroll") for (int _i = 0; _i < 2; ++_i) \
;         __builtin_amdgcn_global_load_lds((const unsigned*)((const char*)(gbase) + (voff)[_i]), (LAS unsigned*)(lds + (bufoff) + ldsw + _i * 8192), 16, 0, 0); } while (0)
; #define PG8_LDA(dst, b, h) do { _Pragma("unroll") for (int m = 0; m < 4; ++m) _Pragma("unroll") for (int k = 0; k < 2; ++k) dst[m][k] = *(const LAS bf16x8*)(lds + PG8_SA(b, h) + aoff + m * 2048 + k * 1024); } while (0)
; #define PG8_LDB(dst, b, h) do { _Pragma("unroll") for (int n = 0; n < 2; ++n) _Pragma("unroll") for (int k = 0; k < 2; ++k) dst[n][k] = *(const LAS bf16x8*)(lds + PG8_SB(b, h) + boff + n * 2048 + k * 1024); } while (0)
; #define PG8_MMA(ai, bj, At, Bt) do { __builtin_amdgcn_s_setprio(1); _Pragma("unroll") for (int m = 0; m < 4; ++m) _Pragma("unroll") for (int n = 0; n < 2; ++n) _Pragma("unroll") for (int k = 0; k < 2; ++k) \
;         acc[ai][bj][m][n] = __builtin_amdgcn_mfma_f32_16x16x32_bf16(Bt[n][k], At[m][k], acc[ai][bj][m][n], 0, 0, 0); __builtin_amdgcn_s_setprio(0); } while (0)
; #define PG8_WAIT_V(n) asm volatile("s_waitcnt vmcnt(" #n ")" ::: "memory")
; #define PG8_WAIT_L(n) asm volatile("s_waitcnt lgkmcnt(" #n ")" ::: "memory")
; #define PG8_BAR __builtin_amdgcn_s_barrier()
; #define PG8_SCHED __builtin_amdgcn_sched_barrier(0)
; template <class Epi, class Sched = StaticOrder, class EpiSub = NoSub, bool FAST = false>
; __device__ __forceinline__ void gemm_phase(LAS unsigned char* lds, const Gemm g, const Sched& S, const Epi& E, const EpiSub& ES = EpiSub()) {
;     ...
;             PG8_WAIT_V(8); PG8_WAIT_L(0); PG8_BAR; PG8_MMA(1, 0, At, B0); PG8_MMA(1, 1, At, B1); PG8_BAR; PG8_SCHED;
;             PG8_LDB(B0, 1, 0); PG8_LDB(B1, 1, 1); PG8_SCHED; PG8_LDA(At, 1, 0); PG8_STAGE(PG8_SA(0, 1), a2 + hstepA, voffA);
;             PG8_WAIT_V(8); PG8_WAIT_L(0); PG8_BAR; PG8_MMA(0, 0, At, B0); PG8_MMA(0, 1, At, B1); PG8_BAR; PG8_SCHED;
	v_mfma_f32_16x16x32_bf16 v[60:63], v[104:107], v[160:163], v[60:63]
	v_mfma_f32_16x16x32_bf16 v[56:59], v[120:123], v[160:163], v[56:59]
	v_mfma_f32_16x16x32_bf16 v[44:47], v[104:107], v[168:171], v[44:47]
	v_mfma_f32_16x16x32_bf16 v[40:43], v[120:123], v[168:171], v[40:43]
	v_mfma_f32_16x16x32_bf16 v[28:31], v[104:107], v[176:179], v[28:31]
	v_mfma_f32_16x16x32_bf16 v[24:27], v[120:123], v[176:179], v[24:27]
	v_mfma_f32_16x16x32_bf16 v[12:15], v[104:107], v[184:187], v[12:15]
	v_mfma_f32_16x16x32_bf16 v[8:11], v[120:123], v[184:187], v[8:11]
	v_mfma_f32_16x16x32_bf16 v[60:63], v[108:111], v[164:167], v[60:63]
	v_mfma_f32_16x16x32_bf16 v[56:59], v[124:127], v[164:167], v[56:59]
	v_mfma_f32_16x16x32_bf16 v[44:47], v[108:111], v[172:175], v[44:47]
	v_mfma_f32_16x16x32_bf16 v[40:43], v[124:127], v[172:175], v[40:43]
	v_mfma_f32_16x16x32_bf16 v[28:31], v[108:111], v[180:183], v[28:31]
	v_mfma_f32_16x16x32_bf16 v[24:27], v[124:127], v[180:183], v[24:27]
	v_mfma_f32_16x16x32_bf16 v[12:15], v[108:111], v[188:191], v[12:15]
	v_mfma_f32_16x16x32_bf16 v[8:11], v[124:127], v[188:191], v[8:11]
	v_mfma_f32_16x16x32_bf16 v[52:55], v[136:139], v[160:163], v[52:55]
	v_mfma_f32_16x16x32_bf16 v[48:51], v[152:155], v[160:163], v[48:51]
	v_mfma_f32_16x16x32_bf16 v[36:39], v[136:139], v[168:171], v[36:39]
	v_mfma_f32_16x16x32_bf16 v[32:35], v[152:155], v[168:171], v[32:35]
	v_mfma_f32_16x16x32_bf16 v[20:23], v[136:139], v[176:179], v[20:23]
	v_mfma_f32_16x16x32_bf16 v[16:19], v[152:155], v[176:179], v[16:19]
	v_mfma_f32_16x16x32_bf16 v[4:7], v[136:139], v[184:187], v[4:7]
	v_mfma_f32_16x16x32_bf16 v[0:3], v[152:155], v[184:187], v[0:3]
	v_mfma_f32_16x16x32_bf16 v[52:55], v[140:143], v[164:167], v[52:55]
	v_mfma_f32_16x16x32_bf16 v[48:51], v[156:159], v[164:167], v[48:51]
	v_mfma_f32_16x16x32_bf16 v[36:39], v[140:143], v[172:175], v[36:39]
	v_mfma_f32_16x16x32_bf16 v[32:35], v[156:159], v[172:175], v[32:35]
	v_mfma_f32_16x16x32_bf16 v[20:23], v[140:143], v[180:183], v[20:23]
	v_mfma_f32_16x16x32_bf16 v[16:19], v[156:159], v[180:183], v[16:19]
	v_mfma_f32_16x16x32_bf16 v[4:7], v[140:143], v[188:191], v[4:7]
	v_mfma_f32_16x16x32_bf16 v[0:3], v[156:159], v[188:191], v[0:3]
	s_barrier
	s_setprio 0
	s_add_i32 s51, 0, 0x18000
	s_add_i32 s70, 0, 0x1c000
	v_add_u32_e32 v124, s51, v221
	v_add_u32_e32 v156, s70, v221
	ds_read_b128 v[104:107], v124
	ds_read_b128 v[108:111], v124 offset:1024
	ds_read_b128 v[120:123], v124 offset:2048
	ds_read_b128 v[124:127], v124 offset:3072
	ds_read_b128 v[136:139], v156
	ds_read_b128 v[140:143], v156 offset:1024
	ds_read_b128 v[152:155], v156 offset:2048
	ds_read_b128 v[156:159], v156 offset:3072
	s_add_u32 s42, s42, 0x80000
	s_addc_u32 s43, s43, 0
	s_mov_b32 m0, s55
	v_lshl_add_u64 v[216:217], s[42:43], 0, v[194:195]
	ds_read_b128 v[160:163], v226 offset:32768
	ds_read_b128 v[164:167], v226 offset:33792
	ds_read_b128 v[168:171], v226 offset:34816
	ds_read_b128 v[172:175], v226 offset:35840
	ds_read_b128 v[176:179], v226 offset:36864
	ds_read_b128 v[180:183], v226 offset:37888
	ds_read_b128 v[184:187], v226 offset:38912
	ds_read_b128 v[188:191], v226 offset:39936
	global_load_lds_dwordx4 v[216:217], off
	v_lshl_add_u64 v[216:217], s[42:43], 0, v[198:199]
	s_mov_b32 m0, s56
	s_nop 0
	global_load_lds_dwordx4 v[216:217], off
	s_waitcnt vmcnt(8)
	s_waitcnt lgkmcnt(0)
	s_setprio 1
	s_barrier
	v_mfma_f32_16x16x32_bf16 v[148:151], v[104:107], v[160:163], v[148:151]
	v_mfma_f32_16x16x32_bf16 v[144:147], v[120:123], v[160:163], v[144:147]
	v_mfma_f32_16x16x32_bf16 v[116:119], v[104:107], v[168:171], v[116:119]
	v_mfma_f32_16x16x32_bf16 v[112:115], v[120:123], v[168:171], v[112:115]
	v_mfma_f32_16x16x32_bf16 v[92:95], v[104:107], v[176:179], v[92:95]
	v_mfma_f32_16x16x32_bf16 v[88:91], v[120:123], v[176:179], v[88:91]
	v_mfma_f32_16x16x32_bf16 v[76:79], v[104:107], v[184:187], v[76:79]
	v_mfma_f32_16x16x32_bf16 v[72:75], v[120:123], v[184:187], v[72:75]
	v_mfma_f32_16x16x32_bf16 v[148:151], v[108:111], v[164:167], v[148:151]
	v_mfma_f32_16x16x32_bf16 v[144:147], v[124:127], v[164:167], v[144:147]
	v_mfma_f32_16x16x32_bf16 v[116:119], v[108:111], v[172:175], v[116:119]
	v_mfma_f32_16x16x32_bf16 v[112:115], v[124:127], v[172:175], v[112:115]
	v_mfma_f32_16x16x32_bf16 v[92:95], v[108:111], v[180:183], v[92:95]
	v_mfma_f32_16x16x32_bf16 v[88:91], v[124:127], v[180:183], v[88:91]
	v_mfma_f32_16x16x32_bf16 v[76:79], v[108:111], v[188:191], v[76:79]
	v_mfma_f32_16x16x32_bf16 v[72:75], v[124:127], v[188:191], v[72:75]
	v_mfma_f32_16x16x32_bf16 v[132:135], v[136:139], v[160:163], v[132:135]
	v_mfma_f32_16x16x32_bf16 v[128:131], v[152:155], v[160:163], v[128:131]
	v_mfma_f32_16x16x32_bf16 v[100:103], v[136:139], v[168:171], v[100:103]
	v_mfma_f32_16x16x32_bf16 v[96:99], v[152:155], v[168:171], v[96:99]
	v_mfma_f32_16x16x32_bf16 v[84:87], v[136:139], v[176:179], v[84:87]
	v_mfma_f32_16x16x32_bf16 v[80:83], v[152:155], v[176:179], v[80:83]
	v_mfma_f32_16x16x32_bf16 v[68:71], v[136:139], v[184:187], v[68:71]
	v_mfma_f32_16x16x32_bf16 v[64:67], v[152:155], v[184:187], v[64:67]
	v_mfma_f32_16x16x32_bf16 v[132:135], v[140:143], v[164:167], v[132:135]
	v_mfma_f32_16x16x32_bf16 v[128:131], v[156:159], v[164:167], v[128:131]
	v_mfma_f32_16x16x32_bf16 v[100:103], v[140:143], v[172:175], v[100:103]
	v_mfma_f32_16x16x32_bf16 v[96:99], v[156:159], v[172:175], v[96:99]
	v_mfma_f32_16x16x32_bf16 v[84:87], v[140:143], v[180:183], v[84:87]
	v_mfma_f32_16x16x32_bf16 v[80:83], v[156:159], v[180:183], v[80:83]
	v_mfma_f32_16x16x32_bf16 v[68:71], v[140:143], v[188:191], v[68:71]
	v_mfma_f32_16x16x32_bf16 v[64:67], v[156:159], v[188:191], v[64:67]
	s_barrier
; #define PG8_STAGE(bufoff, gbase, voff) do { _Pragma("unroll") for (int _i = 0; _i < 2; ++_i) \
;         __builtin_amdgcn_global_load_lds((const unsigned*)((const char*)(gbase) + (voff)[_i]), (LAS unsigned*)(lds + (bufoff) + ldsw + _i * 8192), 16, 0, 0); } while (0)
; #define PG8_LDA(dst, b, h) do { _Pragma("unroll") for (int m = 0; m < 4; ++m) _Pragma("unroll") for (int k = 0; k < 2; ++k) dst[m][k] = *(const LAS bf16x8*)(lds + PG8_SA(b, h) + aoff + m * 2048 + k * 1024); } while (0)
; #define PG8_MMA(ai, bj, At, Bt) do { __builtin_amdgcn_s_setprio(1); _Pragma("unroll") for (int m = 0; m < 4; ++m) _Pragma("unroll") for (int n = 0; n < 2; ++n) _Pragma("unroll") for (int k = 0; k < 2; ++k) \
;         acc[ai][bj][m][n] = __builtin_amdgcn_mfma_f32_16x16x32_bf16(Bt[n][k], At[m][k], acc[ai][bj][m][n], 0, 0, 0); __builtin_amdgcn_s_setprio(0); } while (0)
; #define PG8_WAIT_V(n) asm volatile("s_waitcnt vmcnt(" #n ")" ::: "memory")
; #define PG8_WAIT_L(n) asm volatile("s_waitcnt lgkmcnt(" #n ")" ::: "memory")
; #define PG8_BAR __builtin_amdgcn_s_barrier()
; #define PG8_SCHED __builtin_amdgcn_sched_barrier(0)
; template <class Epi, class Sched = StaticOrder, class EpiSub = NoSub, bool FAST = false>
; __device__ __forceinline__ void gemm_phase(LAS unsigned char* lds, const Gemm g, const Sched& S, const Epi& E, const EpiSub& ES = EpiSub()) {
;     ...
;         for (int t = 0; t < nt; t += 2) {
;     ...
;             PG8_LDA(At, 1, 1); PG8_STAGE(PG8_SB(1, 0), b3, voffB); PG8_STAGE(PG8_SB(1, 1), b3 + hstepB, voffB); PG8_STAGE(PG8_SA(1, 0), a3, voffA);
;             PG8_WAIT_V(8); PG8_WAIT_L(0); PG8_BAR; PG8_MMA(1, 0, At, B0); PG8_MMA(1, 1, At, B1); PG8_BAR; PG8_SCHED;
	s_setprio 0
	s_add_i32 s42, s51, s52
	v_lshl_add_u64 v[208:209], v[208:209], 0, s[12:13]
	s_mov_b32 m0, s42
	ds_read_b128 v[160:163], v226 offset:49152
	ds_read_b128 v[164:167], v226 offset:50176
	ds_read_b128 v[168:171], v226 offset:51200
	ds_read_b128 v[172:175], v226 offset:52224
	ds_read_b128 v[176:179], v226 offset:53248
	ds_read_b128 v[180:183], v226 offset:54272
	ds_read_b128 v[184:187], v226 offset:55296
	ds_read_b128 v[188:191], v226 offset:56320
	global_load_lds_dwordx4 v[208:209], off
	s_add_i32 m0, s42, 0x2000
	s_add_u32 s40, s40, 0x80080
	v_lshl_add_u64 v[208:209], v[210:211], 0, s[12:13]
	s_addc_u32 s41, s41, 0
	s_add_i32 s42, s70, s52
	global_load_lds_dwordx4 v[208:209], off
	v_lshl_add_u64 v[208:209], s[40:41], 0, v[196:197]
	s_mov_b32 m0, s42
	s_nop 0
	global_load_lds_dwordx4 v[208:209], off
	v_lshl_add_u64 v[208:209], s[40:41], 0, v[200:201]
	s_add_i32 m0, s42, 0x2000
	s_nop 0
	global_load_lds_dwordx4 v[208:209], off
	v_lshl_add_u64 v[208:209], v[212:213], 0, s[12:13]
	s_mov_b32 m0, s69
	s_nop 0
	global_load_lds_dwordx4 v[208:209], off
	v_lshl_add_u64 v[208:209], v[214:215], 0, s[12:13]
	s_mov_b32 m0, s74
	s_nop 0
	global_load_lds_dwordx4 v[208:209], off
	s_waitcnt vmcnt(8)
	s_waitcnt lgkmcnt(0)
	s_setprio 1
	s_barrier
	v_mfma_f32_16x16x32_bf16 v[60:63], v[104:107], v[160:163], v[60:63]
	v_mfma_f32_16x16x32_bf16 v[56:59], v[120:123], v[160:163], v[56:59]
	v_mfma_f32_16x16x32_bf16 v[44:47], v[104:107], v[168:171], v[44:47]
	v_mfma_f32_16x16x32_bf16 v[40:43], v[120:123], v[168:171], v[40:43]
	v_mfma_f32_16x16x32_bf16 v[28:31], v[104:107], v[176:179], v[28:31]
	v_mfma_f32_16x16x32_bf16 v[24:27], v[120:123], v[176:179], v[24:27]
	v_mfma_f32_16x16x32_bf16 v[12:15], v[104:107], v[184:187], v[12:15]
	v_mfma_f32_16x16x32_bf16 v[8:11], v[120:123], v[184:187], v[8:11]
	v_mfma_f32_16x16x32_bf16 v[60:63], v[108:111], v[164:167], v[60:63]
	v_mfma_f32_16x16x32_bf16 v[56:59], v[124:127], v[164:167], v[56:59]
	v_mfma_f32_16x16x32_bf16 v[44:47], v[108:111], v[172:175], v[44:47]
	v_mfma_f32_16x16x32_bf16 v[40:43], v[124:127], v[172:175], v[40:43]
	v_mfma_f32_16x16x32_bf16 v[28:31], v[108:111], v[180:183], v[28:31]
	v_mfma_f32_16x16x32_bf16 v[24:27], v[124:127], v[180:183], v[24:27]
	v_mfma_f32_16x16x32_bf16 v[12:15], v[108:111], v[188:191], v[12:15]
	v_mfma_f32_16x16x32_bf16 v[8:11], v[124:127], v[188:191], v[8:11]
	v_mfma_f32_16x16x32_bf16 v[52:55], v[136:139], v[160:163], v[52:55]
	v_mfma_f32_16x16x32_bf16 v[48:51], v[152:155], v[160:163], v[48:51]
	v_mfma_f32_16x16x32_bf16 v[36:39], v[136:139], v[168:171], v[36:39]
	v_mfma_f32_16x16x32_bf16 v[32:35], v[152:155], v[168:171], v[32:35]
	v_mfma_f32_16x16x32_bf16 v[20:23], v[136:139], v[176:179], v[20:23]
	v_mfma_f32_16x16x32_bf16 v[16:19], v[152:155], v[176:179], v[16:19]
	v_mfma_f32_16x16x32_bf16 v[4:7], v[136:139], v[184:187], v[4:7]
	v_mfma_f32_16x16x32_bf16 v[0:3], v[152:155], v[184:187], v[0:3]
	v_mfma_f32_16x16x32_bf16 v[52:55], v[140:143], v[164:167], v[52:55]
	v_mfma_f32_16x16x32_bf16 v[48:51], v[156:159], v[164:167], v[48:51]
	v_mfma_f32_16x16x32_bf16 v[36:39], v[140:143], v[172:175], v[36:39]
	v_mfma_f32_16x16x32_bf16 v[32:35], v[156:159], v[172:175], v[32:35]
	v_mfma_f32_16x16x32_bf16 v[20:23], v[140:143], v[180:183], v[20:23]
	v_mfma_f32_16x16x32_bf16 v[16:19], v[156:159], v[180:183], v[16:19]
	v_mfma_f32_16x16x32_bf16 v[4:7], v[140:143], v[188:191], v[4:7]
	v_mfma_f32_16x16x32_bf16 v[0:3], v[156:159], v[188:191], v[0:3]
	s_barrier
	s_setprio 0
	s_add_u32 s38, s38, 0x100
	s_addc_u32 s39, s39, 0
	s_add_u32 s48, s48, 0x100
	s_addc_u32 s49, s49, 0
	s_cmp_ge_u32 s50, s31
	s_mov_b32 s42, s50
	s_cbranch_scc0 .LBB0_632
	s_and_b64 vcc, exec, s[14:15]
	s_cbranch_vccz .LBB0_635
	s_barrier

; #define PG8_STAGE(bufoff, gbase, voff) do { _Pragma("unroll") for (int _i = 0; _i < 2; ++_i) \
;         __builtin_amdgcn_global_load_lds((const unsigned*)((const char*)(gbase) + (voff)[_i]), (LAS unsigned*)(lds + (bufoff) + ldsw + _i * 8192), 16, 0, 0); } while (0)
; #define PG8_LDA(dst, b, h) do { _Pragma("unroll") for (int m = 0; m < 4; ++m) _Pragma("unroll") for (int k = 0; k < 2; ++k) dst[m][k] = *(const LAS bf16x8*)(lds + PG8_SA(b, h) + aoff + m * 2048 + k * 1024); } while (0)
; #define PG8_LDB(dst, b, h) do { _Pragma("unroll") for (int n = 0; n < 2; ++n) _Pragma("unroll") for (int k = 0; k < 2; ++k) dst[n][k] = *(const LAS bf16x8*)(lds + PG8_SB(b, h) + boff + n * 2048 + k * 1024); } while (0)
; #define PG8_MMA(ai, bj, At, Bt) do { __builtin_amdgcn_s_setprio(1); _Pragma("unroll") for (int m = 0; m < 4; ++m) _Pragma("unroll") for (int n = 0; n < 2; ++n) _Pragma("unroll") for (int k = 0; k < 2; ++k) \
;         acc[ai][bj][m][n] = __builtin_amdgcn_mfma_f32_16x16x32_bf16(Bt[n][k], At[m][k], acc[ai][bj][m][n], 0, 0, 0); __builtin_amdgcn_s_setprio(0); } while (0)
; #define PG8_WAIT_V(n) asm volatile("s_waitcnt vmcnt(" #n ")" ::: "memory")
; #define PG8_WAIT_L(n) asm volatile("s_waitcnt lgkmcnt(" #n ")" ::: "memory")
; #define PG8_BAR __builtin_amdgcn_s_barrier()
; template <class Epi, class Sched = StaticOrder, class EpiSub = NoSub, bool FAST = false>
; __device__ __forceinline__ void gemm_phase(LAS unsigned char* lds, const Gemm g, const Sched& S, const Epi& E, const EpiSub& ES = EpiSub()) {
;     ...
;             const bool last = (t == nt - 2);
;             const char* a1 = cA + (size_t)(t + 1) * kstep;
;             const char* a2 = last ? nA : cA + (size_t)(t + 2) * kstep; const char* b2 = last ? nB : cB + (size_t)(t + 2) * kstep;
;             const char* a3 = a2 + kstep; const char* b3 = b2 + kstep;
;             if constexpr (FAST && PG8_SP2) {
;             PG8_LDB(B0, 0, 0); PG8_LDB(B1, 0, 1); PG8_SCHED; PG8_LDA(At, 0, 0); PG8_STAGE(PG8_SA(1, 1), a1 + hstepA, voffA);
;             PG8_WAIT_V(8); PG8_WAIT_L(0); PG8_BAR; PG8_MMA(0, 0, At, B0); PG8_MMA(0, 1, At, B1); PG8_BAR; PG8_SCHED;
;             PG8_LDA(At, 0, 1); PG8_STAGE(PG8_SB(0, 0), b2, voffB); PG8_STAGE(PG8_SB(0, 1), b2 + hstepB, voffB); PG8_STAGE(PG8_SA(0, 0), a2, voffA);
;             PG8_WAIT_V(8); PG8_WAIT_L(0); PG8_BAR; PG8_MMA(1, 0, At, B0); PG8_MMA(1, 1, At, B1); PG8_BAR; PG8_SCHED;
.LBB0_769:
	ds_read_b128 v[96:99], v215
	ds_read_b128 v[100:103], v215 offset:1024
	ds_read_b128 v[112:115], v215 offset:2048
	ds_read_b128 v[116:119], v215 offset:3072
	ds_read_b128 v[144:147], v216
	ds_read_b128 v[148:151], v216 offset:1024
	ds_read_b128 v[152:155], v216 offset:2048
	ds_read_b128 v[156:159], v216 offset:3072
	s_add_i32 s72, s42, 2
	s_add_u32 s40, s38, 0xfff80080
	s_addc_u32 s41, s39, -1
	s_cmp_eq_u32 s33, s42
	s_cselect_b32 s42, s5, s40
	s_cselect_b32 s43, s1, s41
	s_cselect_b32 s41, s19, s71
	s_cselect_b32 s40, s21, s70
	v_lshl_add_u64 v[208:209], s[38:39], 0, v[194:195]
	s_add_i32 m0, s48, 0xc000
	ds_read_b128 v[160:163], v217
	ds_read_b128 v[164:167], v217 offset:1024
	ds_read_b128 v[168:171], v217 offset:2048
	ds_read_b128 v[172:175], v217 offset:3072
	ds_read_b128 v[176:179], v217 offset:4096
	ds_read_b128 v[180:183], v217 offset:5120
	ds_read_b128 v[200:203], v217 offset:6144
	ds_read_b128 v[204:207], v217 offset:7168
	global_load_lds_dwordx4 v[208:209], off
	v_lshl_add_u64 v[208:209], s[38:39], 0, v[196:197]
	s_add_i32 m0, s48, 0xe000
	s_nop 0
	global_load_lds_dwordx4 v[208:209], off
	s_waitcnt vmcnt(8)
	s_waitcnt lgkmcnt(0)
	s_setprio 1
	s_barrier
	v_mfma_f32_16x16x32_bf16 v[140:143], v[96:99], v[160:163], v[140:143]
	v_mfma_f32_16x16x32_bf16 v[136:139], v[112:115], v[160:163], v[136:139]
	v_mfma_f32_16x16x32_bf16 v[124:127], v[96:99], v[168:171], v[124:127]
	v_mfma_f32_16x16x32_bf16 v[120:123], v[112:115], v[168:171], v[120:123]
	v_mfma_f32_16x16x32_bf16 v[92:95], v[96:99], v[176:179], v[92:95]
	v_mfma_f32_16x16x32_bf16 v[88:91], v[112:115], v[176:179], v[88:91]
	v_mfma_f32_16x16x32_bf16 v[76:79], v[96:99], v[200:203], v[76:79]
	v_mfma_f32_16x16x32_bf16 v[72:75], v[112:115], v[200:203], v[72:75]
	v_mfma_f32_16x16x32_bf16 v[140:143], v[100:103], v[164:167], v[140:143]
	v_mfma_f32_16x16x32_bf16 v[136:139], v[116:119], v[164:167], v[136:139]
	v_mfma_f32_16x16x32_bf16 v[124:127], v[100:103], v[172:175], v[124:127]
	v_mfma_f32_16x16x32_bf16 v[120:123], v[116:119], v[172:175], v[120:123]
	v_mfma_f32_16x16x32_bf16 v[92:95], v[100:103], v[180:183], v[92:95]
	v_mfma_f32_16x16x32_bf16 v[88:91], v[116:119], v[180:183], v[88:91]
	v_mfma_f32_16x16x32_bf16 v[76:79], v[100:103], v[204:207], v[76:79]
	v_mfma_f32_16x16x32_bf16 v[72:75], v[116:119], v[204:207], v[72:75]
	v_mfma_f32_16x16x32_bf16 v[132:135], v[144:147], v[160:163], v[132:135]
	v_mfma_f32_16x16x32_bf16 v[128:131], v[152:155], v[160:163], v[128:131]
	v_mfma_f32_16x16x32_bf16 v[108:111], v[144:147], v[168:171], v[108:111]
	v_mfma_f32_16x16x32_bf16 v[104:107], v[152:155], v[168:171], v[104:107]
	v_mfma_f32_16x16x32_bf16 v[84:87], v[144:147], v[176:179], v[84:87]
	v_mfma_f32_16x16x32_bf16 v[80:83], v[152:155], v[176:179], v[80:83]
	v_mfma_f32_16x16x32_bf16 v[68:71], v[144:147], v[200:203], v[68:71]
	v_mfma_f32_16x16x32_bf16 v[64:67], v[152:155], v[200:203], v[64:67]
	v_mfma_f32_16x16x32_bf16 v[132:135], v[148:151], v[164:167], v[132:135]
	v_mfma_f32_16x16x32_bf16 v[128:131], v[156:159], v[164:167], v[128:131]
	v_mfma_f32_16x16x32_bf16 v[108:111], v[148:151], v[172:175], v[108:111]
	v_mfma_f32_16x16x32_bf16 v[104:107], v[156:159], v[172:175], v[104:107]
	v_mfma_f32_16x16x32_bf16 v[84:87], v[148:151], v[180:183], v[84:87]
	v_mfma_f32_16x16x32_bf16 v[80:83], v[156:159], v[180:183], v[80:83]
	v_mfma_f32_16x16x32_bf16 v[68:71], v[148:151], v[204:207], v[68:71]
	v_mfma_f32_16x16x32_bf16 v[64:67], v[156:159], v[204:207], v[64:67]
	s_barrier
	s_setprio 0
	s_add_i32 s73, s58, s17
	v_lshl_add_u64 v[208:209], s[40:41], 0, v[186:187]
	s_mov_b32 m0, s73
	ds_read_b128 v[160:163], v217 offset:16384
	ds_read_b128 v[164:167], v217 offset:17408
	ds_read_b128 v[168:171], v217 offset:18432
	ds_read_b128 v[172:175], v217 offset:19456
	ds_read_b128 v[176:179], v217 offset:20480
	ds_read_b128 v[180:183], v217 offset:21504
	ds_read_b128 v[200:203], v217 offset:22528
	ds_read_b128 v[204:207], v217 offset:23552
	global_load_lds_dwordx4 v[208:209], off
	s_add_i32 m0, s73, 0x2000
	s_add_u32 s76, s40, 0x80000
	v_lshl_add_u64 v[210:211], s[40:41], 0, v[190:191]
	s_addc_u32 s77, s41, 0
	s_add_i32 s73, s59, s17
	global_load_lds_dwordx4 v[210:211], off
	v_lshl_add_u64 v[218:219], s[76:77], 0, v[186:187]
	s_mov_b32 m0, s73
	v_lshl_add_u64 v[220:221], s[42:43], 0, v[188:189]
	global_load_lds_dwordx4 v[218:219], off
	v_lshl_add_u64 v[218:219], s[76:77], 0, v[190:191]
	s_add_i32 m0, s73, 0x2000
	s_nop 0
	global_load_lds_dwordx4 v[218:219], off
	v_lshl_add_u64 v[218:219], s[42:43], 0, v[184:185]
	s_mov_b32 m0, s48
	s_nop 0
	global_load_lds_dwordx4 v[218:219], off
	s_mov_b32 m0, s49
	s_nop 0
	global_load_lds_dwordx4 v[220:221], off
	s_waitcnt vmcnt(8)
	s_waitcnt lgkmcnt(0)
	s_setprio 1
	s_barrier
; #define PG8_STAGE(bufoff, gbase, voff) do { _Pragma("unroll") for (int _i = 0; _i < 2; ++_i) \
;         __builtin_amdgcn_global_load_lds((const unsigned*)((const char*)(gbase) + (voff)[_i]), (LAS unsigned*)(lds + (bufoff) + ldsw + _i * 8192), 16, 0, 0); } while (0)
; #define PG8_LDA(dst, b, h) do { _Pragma("unroll") for (int m = 0; m < 4; ++m) _Pragma("unroll") for (int k = 0; k < 2; ++k) dst[m][k] = *(const LAS bf16x8*)(lds + PG8_SA(b, h) + aoff + m * 2048 + k * 1024); } while (0)
; #define PG8_LDB(dst, b, h) do { _Pragma("unroll") for (int n = 0; n < 2; ++n) _Pragma("unroll") for (int k = 0; k < 2; ++k) dst[n][k] = *(const LAS bf16x8*)(lds + PG8_SB(b, h) + boff + n * 2048 + k * 1024); } while (0)
; #define PG8_MMA(ai, bj, At, Bt) do { __builtin_amdgcn_s_setprio(1); _Pragma("unroll") for (int m = 0; m < 4; ++m) _Pragma("unroll") for (int n = 0; n < 2; ++n) _Pragma("unroll") for (int k = 0; k < 2; ++k) \
;         acc[ai][bj][m][n] = __builtin_amdgcn_mfma_f32_16x16x32_bf16(Bt[n][k], At[m][k], acc[ai][bj][m][n], 0, 0, 0); __builtin_amdgcn_s_setprio(0); } while (0)
; #define PG8_WAIT_V(n) asm volatile("s_waitcnt vmcnt(" #n ")" ::: "memory")
; #define PG8_WAIT_L(n) asm volatile("s_waitcnt lgkmcnt(" #n ")" ::: "memory")
; #define PG8_BAR __builtin_amdgcn_s_barrier()
; #define PG8_SCHED __builtin_amdgcn_sched_barrier(0)
; template <class Epi, class Sched = StaticOrder, class EpiSub = NoSub, bool FAST = false>
; __device__ __forceinline__ void gemm_phase(LAS unsigned char* lds, const Gemm g, const Sched& S, const Epi& E, const EpiSub& ES = EpiSub()) {
;     ...
;             PG8_WAIT_V(8); PG8_WAIT_L(0); PG8_BAR; PG8_MMA(1, 0, At, B0); PG8_MMA(1, 1, At, B1); PG8_BAR; PG8_SCHED;
;             PG8_LDB(B0, 1, 0); PG8_LDB(B1, 1, 1); PG8_SCHED; PG8_LDA(At, 1, 0); PG8_STAGE(PG8_SA(0, 1), a2 + hstepA, voffA);
;             PG8_WAIT_V(8); PG8_WAIT_L(0); PG8_BAR; PG8_MMA(0, 0, At, B0); PG8_MMA(0, 1, At, B1); PG8_BAR; PG8_SCHED;
	v_mfma_f32_16x16x32_bf16 v[60:63], v[96:99], v[160:163], v[60:63]
	v_mfma_f32_16x16x32_bf16 v[56:59], v[112:115], v[160:163], v[56:59]
	v_mfma_f32_16x16x32_bf16 v[44:47], v[96:99], v[168:171], v[44:47]
	v_mfma_f32_16x16x32_bf16 v[40:43], v[112:115], v[168:171], v[40:43]
	v_mfma_f32_16x16x32_bf16 v[28:31], v[96:99], v[176:179], v[28:31]
	v_mfma_f32_16x16x32_bf16 v[24:27], v[112:115], v[176:179], v[24:27]
	v_mfma_f32_16x16x32_bf16 v[12:15], v[96:99], v[200:203], v[12:15]
	v_mfma_f32_16x16x32_bf16 v[8:11], v[112:115], v[200:203], v[8:11]
	v_mfma_f32_16x16x32_bf16 v[60:63], v[100:103], v[164:167], v[60:63]
	v_mfma_f32_16x16x32_bf16 v[56:59], v[116:119], v[164:167], v[56:59]
	v_mfma_f32_16x16x32_bf16 v[44:47], v[100:103], v[172:175], v[44:47]
	v_mfma_f32_16x16x32_bf16 v[40:43], v[116:119], v[172:175], v[40:43]
	v_mfma_f32_16x16x32_bf16 v[28:31], v[100:103], v[180:183], v[28:31]
	v_mfma_f32_16x16x32_bf16 v[24:27], v[116:119], v[180:183], v[24:27]
	v_mfma_f32_16x16x32_bf16 v[12:15], v[100:103], v[204:207], v[12:15]
	v_mfma_f32_16x16x32_bf16 v[8:11], v[116:119], v[204:207], v[8:11]
	v_mfma_f32_16x16x32_bf16 v[52:55], v[144:147], v[160:163], v[52:55]
	v_mfma_f32_16x16x32_bf16 v[48:51], v[152:155], v[160:163], v[48:51]
	v_mfma_f32_16x16x32_bf16 v[36:39], v[144:147], v[168:171], v[36:39]
	v_mfma_f32_16x16x32_bf16 v[32:35], v[152:155], v[168:171], v[32:35]
	v_mfma_f32_16x16x32_bf16 v[20:23], v[144:147], v[176:179], v[20:23]
	v_mfma_f32_16x16x32_bf16 v[16:19], v[152:155], v[176:179], v[16:19]
	v_mfma_f32_16x16x32_bf16 v[4:7], v[144:147], v[200:203], v[4:7]
	v_mfma_f32_16x16x32_bf16 v[0:3], v[152:155], v[200:203], v[0:3]
	v_mfma_f32_16x16x32_bf16 v[52:55], v[148:151], v[164:167], v[52:55]
	v_mfma_f32_16x16x32_bf16 v[48:51], v[156:159], v[164:167], v[48:51]
	v_mfma_f32_16x16x32_bf16 v[36:39], v[148:151], v[172:175], v[36:39]
	v_mfma_f32_16x16x32_bf16 v[32:35], v[156:159], v[172:175], v[32:35]
	v_mfma_f32_16x16x32_bf16 v[20:23], v[148:151], v[180:183], v[20:23]
	v_mfma_f32_16x16x32_bf16 v[16:19], v[156:159], v[180:183], v[16:19]
	v_mfma_f32_16x16x32_bf16 v[4:7], v[148:151], v[204:207], v[4:7]
	v_mfma_f32_16x16x32_bf16 v[0:3], v[156:159], v[204:207], v[0:3]
	s_barrier
	s_setprio 0
	s_add_i32 s73, 0, 0x18000
	s_add_i32 s76, 0, 0x1c000
	v_add_u32_e32 v116, s73, v212
	v_add_u32_e32 v156, s76, v212
	ds_read_b128 v[96:99], v116
	ds_read_b128 v[100:103], v116 offset:1024
	ds_read_b128 v[112:115], v116 offset:2048
	ds_read_b128 v[116:119], v116 offset:3072
	ds_read_b128 v[144:147], v156
	ds_read_b128 v[148:151], v156 offset:1024
	ds_read_b128 v[152:155], v156 offset:2048
	ds_read_b128 v[156:159], v156 offset:3072
	s_add_u32 s42, s42, 0x80000
	s_addc_u32 s43, s43, 0
	s_mov_b32 m0, s50
	v_lshl_add_u64 v[222:223], s[42:43], 0, v[184:185]
	ds_read_b128 v[160:163], v217 offset:32768
	ds_read_b128 v[164:167], v217 offset:33792
	ds_read_b128 v[168:171], v217 offset:34816
	ds_read_b128 v[172:175], v217 offset:35840
	ds_read_b128 v[176:179], v217 offset:36864
	ds_read_b128 v[180:183], v217 offset:37888
	ds_read_b128 v[200:203], v217 offset:38912
	ds_read_b128 v[204:207], v217 offset:39936
	global_load_lds_dwordx4 v[222:223], off
	v_lshl_add_u64 v[222:223], s[42:43], 0, v[188:189]
	s_mov_b32 m0, s51
	s_nop 0
	global_load_lds_dwordx4 v[222:223], off
	s_waitcnt vmcnt(8)
	s_waitcnt lgkmcnt(0)
	s_setprio 1
	s_barrier
	v_mfma_f32_16x16x32_bf16 v[140:143], v[96:99], v[160:163], v[140:143]
	v_mfma_f32_16x16x32_bf16 v[136:139], v[112:115], v[160:163], v[136:139]
	v_mfma_f32_16x16x32_bf16 v[124:127], v[96:99], v[168:171], v[124:127]
	v_mfma_f32_16x16x32_bf16 v[120:123], v[112:115], v[168:171], v[120:123]
	v_mfma_f32_16x16x32_bf16 v[92:95], v[96:99], v[176:179], v[92:95]
	v_mfma_f32_16x16x32_bf16 v[88:91], v[112:115], v[176:179], v[88:91]
	v_mfma_f32_16x16x32_bf16 v[76:79], v[96:99], v[200:203], v[76:79]
	v_mfma_f32_16x16x32_bf16 v[72:75], v[112:115], v[200:203], v[72:75]
	v_mfma_f32_16x16x32_bf16 v[140:143], v[100:103], v[164:167], v[140:143]
	v_mfma_f32_16x16x32_bf16 v[136:139], v[116:119], v[164:167], v[136:139]
	v_mfma_f32_16x16x32_bf16 v[124:127], v[100:103], v[172:175], v[124:127]
	v_mfma_f32_16x16x32_bf16 v[120:123], v[116:119], v[172:175], v[120:123]
	v_mfma_f32_16x16x32_bf16 v[92:95], v[100:103], v[180:183], v[92:95]
	v_mfma_f32_16x16x32_bf16 v[88:91], v[116:119], v[180:183], v[88:91]
	v_mfma_f32_16x16x32_bf16 v[76:79], v[100:103], v[204:207], v[76:79]
	v_mfma_f32_16x16x32_bf16 v[72:75], v[116:119], v[204:207], v[72:75]
	v_mfma_f32_16x16x32_bf16 v[132:135], v[144:147], v[160:163], v[132:135]
	v_mfma_f32_16x16x32_bf16 v[128:131], v[152:155], v[160:163], v[128:131]
	v_mfma_f32_16x16x32_bf16 v[108:111], v[144:147], v[168:171], v[108:111]
	v_mfma_f32_16x16x32_bf16 v[104:107], v[152:155], v[168:171], v[104:107]
	v_mfma_f32_16x16x32_bf16 v[84:87], v[144:147], v[176:179], v[84:87]
	v_mfma_f32_16x16x32_bf16 v[80:83], v[152:155], v[176:179], v[80:83]
	v_mfma_f32_16x16x32_bf16 v[68:71], v[144:147], v[200:203], v[68:71]
	v_mfma_f32_16x16x32_bf16 v[64:67], v[152:155], v[200:203], v[64:67]
	v_mfma_f32_16x16x32_bf16 v[132:135], v[148:151], v[164:167], v[132:135]
	v_mfma_f32_16x16x32_bf16 v[128:131], v[156:159], v[164:167], v[128:131]
	v_mfma_f32_16x16x32_bf16 v[108:111], v[148:151], v[172:175], v[108:111]
	v_mfma_f32_16x16x32_bf16 v[104:107], v[156:159], v[172:175], v[104:107]
	v_mfma_f32_16x16x32_bf16 v[84:87], v[148:151], v[180:183], v[84:87]
	v_mfma_f32_16x16x32_bf16 v[80:83], v[156:159], v[180:183], v[80:83]
	v_mfma_f32_16x16x32_bf16 v[68:71], v[148:151], v[204:207], v[68:71]
	v_mfma_f32_16x16x32_bf16 v[64:67], v[156:159], v[204:207], v[64:67]
	s_barrier
; #define PG8_STAGE(bufoff, gbase, voff) do { _Pragma("unroll") for (int _i = 0; _i < 2; ++_i) \
;         __builtin_amdgcn_global_load_lds((const unsigned*)((const char*)(gbase) + (voff)[_i]), (LAS unsigned*)(lds + (bufoff) + ldsw + _i * 8192), 16, 0, 0); } while (0)
; #define PG8_LDA(dst, b, h) do { _Pragma("unroll") for (int m = 0; m < 4; ++m) _Pragma("unroll") for (int k = 0; k < 2; ++k) dst[m][k] = *(const LAS bf16x8*)(lds + PG8_SA(b, h) + aoff + m * 2048 + k * 1024); } while (0)
; #define PG8_MMA(ai, bj, At, Bt) do { __builtin_amdgcn_s_setprio(1); _Pragma("unroll") for (int m = 0; m < 4; ++m) _Pragma("unroll") for (int n = 0; n < 2; ++n) _Pragma("unroll") for (int k = 0; k < 2; ++k) \
;         acc[ai][bj][m][n] = __builtin_amdgcn_mfma_f32_16x16x32_bf16(Bt[n][k], At[m][k], acc[ai][bj][m][n], 0, 0, 0); __builtin_amdgcn_s_setprio(0); } while (0)
; #define PG8_WAIT_V(n) asm volatile("s_waitcnt vmcnt(" #n ")" ::: "memory")
; #define PG8_WAIT_L(n) asm volatile("s_waitcnt lgkmcnt(" #n ")" ::: "memory")
; #define PG8_BAR __builtin_amdgcn_s_barrier()
; #define PG8_SCHED __builtin_amdgcn_sched_barrier(0)
; template <class Epi, class Sched = StaticOrder, class EpiSub = NoSub, bool FAST = false>
; __device__ __forceinline__ void gemm_phase(LAS unsigned char* lds, const Gemm g, const Sched& S, const Epi& E, const EpiSub& ES = EpiSub()) {
;     ...
;         for (int t = 0; t < nt; t += 2) {
;     ...
;             PG8_LDA(At, 1, 1); PG8_STAGE(PG8_SB(1, 0), b3, voffB); PG8_STAGE(PG8_SB(1, 1), b3 + hstepB, voffB); PG8_STAGE(PG8_SA(1, 0), a3, voffA);
;             PG8_WAIT_V(8); PG8_WAIT_L(0); PG8_BAR; PG8_MMA(1, 0, At, B0); PG8_MMA(1, 1, At, B1); PG8_BAR; PG8_SCHED;
	s_setprio 0
	s_add_i32 s42, s73, s17
	v_lshl_add_u64 v[208:209], v[208:209], 0, s[12:13]
	s_mov_b32 m0, s42
	ds_read_b128 v[160:163], v217 offset:49152
	ds_read_b128 v[164:167], v217 offset:50176
	ds_read_b128 v[168:171], v217 offset:51200
	ds_read_b128 v[172:175], v217 offset:52224
	ds_read_b128 v[176:179], v217 offset:53248
	ds_read_b128 v[180:183], v217 offset:54272
	ds_read_b128 v[200:203], v217 offset:55296
	ds_read_b128 v[204:207], v217 offset:56320
	global_load_lds_dwordx4 v[208:209], off
	s_add_i32 m0, s42, 0x2000
	s_add_u32 s40, s40, 0x80080
	v_lshl_add_u64 v[208:209], v[210:211], 0, s[12:13]
	s_addc_u32 s41, s41, 0
	s_add_i32 s42, s76, s17
	global_load_lds_dwordx4 v[208:209], off
	v_lshl_add_u64 v[208:209], s[40:41], 0, v[186:187]
	s_mov_b32 m0, s42
	s_nop 0
	global_load_lds_dwordx4 v[208:209], off
	v_lshl_add_u64 v[208:209], s[40:41], 0, v[190:191]
	s_add_i32 m0, s42, 0x2000
	s_nop 0
	global_load_lds_dwordx4 v[208:209], off
	v_lshl_add_u64 v[208:209], v[218:219], 0, s[12:13]
	s_mov_b32 m0, s55
	s_nop 0
	global_load_lds_dwordx4 v[208:209], off
	v_lshl_add_u64 v[208:209], v[220:221], 0, s[12:13]
	s_mov_b32 m0, s56
	s_nop 0
	global_load_lds_dwordx4 v[208:209], off
	s_waitcnt vmcnt(8)
	s_waitcnt lgkmcnt(0)
	s_setprio 1
	s_barrier
	v_mfma_f32_16x16x32_bf16 v[60:63], v[96:99], v[160:163], v[60:63]
	v_mfma_f32_16x16x32_bf16 v[56:59], v[112:115], v[160:163], v[56:59]
	v_mfma_f32_16x16x32_bf16 v[44:47], v[96:99], v[168:171], v[44:47]
	v_mfma_f32_16x16x32_bf16 v[40:43], v[112:115], v[168:171], v[40:43]
	v_mfma_f32_16x16x32_bf16 v[28:31], v[96:99], v[176:179], v[28:31]
	v_mfma_f32_16x16x32_bf16 v[24:27], v[112:115], v[176:179], v[24:27]
	v_mfma_f32_16x16x32_bf16 v[12:15], v[96:99], v[200:203], v[12:15]
	v_mfma_f32_16x16x32_bf16 v[8:11], v[112:115], v[200:203], v[8:11]
	v_mfma_f32_16x16x32_bf16 v[60:63], v[100:103], v[164:167], v[60:63]
	v_mfma_f32_16x16x32_bf16 v[56:59], v[116:119], v[164:167], v[56:59]
	v_mfma_f32_16x16x32_bf16 v[44:47], v[100:103], v[172:175], v[44:47]
	v_mfma_f32_16x16x32_bf16 v[40:43], v[116:119], v[172:175], v[40:43]
	v_mfma_f32_16x16x32_bf16 v[28:31], v[100:103], v[180:183], v[28:31]
	v_mfma_f32_16x16x32_bf16 v[24:27], v[116:119], v[180:183], v[24:27]
	v_mfma_f32_16x16x32_bf16 v[12:15], v[100:103], v[204:207], v[12:15]
	v_mfma_f32_16x16x32_bf16 v[8:11], v[116:119], v[204:207], v[8:11]
	v_mfma_f32_16x16x32_bf16 v[52:55], v[144:147], v[160:163], v[52:55]
	v_mfma_f32_16x16x32_bf16 v[48:51], v[152:155], v[160:163], v[48:51]
	v_mfma_f32_16x16x32_bf16 v[36:39], v[144:147], v[168:171], v[36:39]
	v_mfma_f32_16x16x32_bf16 v[32:35], v[152:155], v[168:171], v[32:35]
	v_mfma_f32_16x16x32_bf16 v[20:23], v[144:147], v[176:179], v[20:23]
	v_mfma_f32_16x16x32_bf16 v[16:19], v[152:155], v[176:179], v[16:19]
	v_mfma_f32_16x16x32_bf16 v[4:7], v[144:147], v[200:203], v[4:7]
	v_mfma_f32_16x16x32_bf16 v[0:3], v[152:155], v[200:203], v[0:3]
	v_mfma_f32_16x16x32_bf16 v[52:55], v[148:151], v[164:167], v[52:55]
	v_mfma_f32_16x16x32_bf16 v[48:51], v[156:159], v[164:167], v[48:51]
	v_mfma_f32_16x16x32_bf16 v[36:39], v[148:151], v[172:175], v[36:39]
	v_mfma_f32_16x16x32_bf16 v[32:35], v[156:159], v[172:175], v[32:35]
	v_mfma_f32_16x16x32_bf16 v[20:23], v[148:151], v[180:183], v[20:23]
	v_mfma_f32_16x16x32_bf16 v[16:19], v[156:159], v[180:183], v[16:19]
	v_mfma_f32_16x16x32_bf16 v[4:7], v[148:151], v[204:207], v[4:7]
	v_mfma_f32_16x16x32_bf16 v[0:3], v[156:159], v[204:207], v[0:3]
	s_barrier
	s_setprio 0
	s_add_u32 s38, s38, 0x100
	s_addc_u32 s39, s39, 0
	s_add_u32 s70, s70, 0x100
	s_addc_u32 s71, s71, 0
	s_cmp_ge_u32 s72, s29
	s_mov_b32 s42, s72
	s_cbranch_scc0 .LBB0_769
	s_and_b64 vcc, exec, s[14:15]
	s_cbranch_vccz .LBB0_772
	s_barrier

; #define PG8_STAGE(bufoff, gbase, voff) do { _Pragma("unroll") for (int _i = 0; _i < 2; ++_i) \
;         __builtin_amdgcn_global_load_lds((const unsigned*)((const char*)(gbase) + (voff)[_i]), (LAS unsigned*)(lds + (bufoff) + ldsw + _i * 8192), 16, 0, 0); } while (0)
; #define PG8_LDA(dst, b, h) do { _Pragma("unroll") for (int m = 0; m < 4; ++m) _Pragma("unroll") for (int k = 0; k < 2; ++k) dst[m][k] = *(const LAS bf16x8*)(lds + PG8_SA(b, h) + aoff + m * 2048 + k * 1024); } while (0)
; #define PG8_LDB(dst, b, h) do { _Pragma("unroll") for (int n = 0; n < 2; ++n) _Pragma("unroll") for (int k = 0; k < 2; ++k) dst[n][k] = *(const LAS bf16x8*)(lds + PG8_SB(b, h) + boff + n * 2048 + k * 1024); } while (0)
; #define PG8_MMA(ai, bj, At, Bt) do { __builtin_amdgcn_s_setprio(1); _Pragma("unroll") for (int m = 0; m < 4; ++m) _Pragma("unroll") for (int n = 0; n < 2; ++n) _Pragma("unroll") for (int k = 0; k < 2; ++k) \
;         acc[ai][bj][m][n] = __builtin_amdgcn_mfma_f32_16x16x32_bf16(Bt[n][k], At[m][k], acc[ai][bj][m][n], 0, 0, 0); __builtin_amdgcn_s_setprio(0); } while (0)
; #define PG8_WAIT_V(n) asm volatile("s_waitcnt vmcnt(" #n ")" ::: "memory")
; #define PG8_WAIT_L(n) asm volatile("s_waitcnt lgkmcnt(" #n ")" ::: "memory")
; #define PG8_BAR __builtin_amdgcn_s_barrier()
; template <class Epi, class Sched = StaticOrder, class EpiSub = NoSub, bool FAST = false>
; __device__ __forceinline__ void gemm_phase(LAS unsigned char* lds, const Gemm g, const Sched& S, const Epi& E, const EpiSub& ES = EpiSub()) {
;     ...
;             const bool last = (t == nt - 2);
;             const char* a1 = cA + (size_t)(t + 1) * kstep;
;             const char* a2 = last ? nA : cA + (size_t)(t + 2) * kstep; const char* b2 = last ? nB : cB + (size_t)(t + 2) * kstep;
;             const char* a3 = a2 + kstep; const char* b3 = b2 + kstep;
;             if constexpr (FAST && PG8_SP2) {
;             PG8_LDB(B0, 0, 0); PG8_LDB(B1, 0, 1); PG8_SCHED; PG8_LDA(At, 0, 0); PG8_STAGE(PG8_SA(1, 1), a1 + hstepA, voffA);
;             PG8_WAIT_V(8); PG8_WAIT_L(0); PG8_BAR; PG8_MMA(0, 0, At, B0); PG8_MMA(0, 1, At, B1); PG8_BAR; PG8_SCHED;
;             PG8_LDA(At, 0, 1); PG8_STAGE(PG8_SB(0, 0), b2, voffB); PG8_STAGE(PG8_SB(0, 1), b2 + hstepB, voffB); PG8_STAGE(PG8_SA(0, 0), a2, voffA);
;             PG8_WAIT_V(8); PG8_WAIT_L(0); PG8_BAR; PG8_MMA(1, 0, At, B0); PG8_MMA(1, 1, At, B1); PG8_BAR; PG8_SCHED;
.LBB0_985:
	ds_read_b128 v[150:153], v147
	ds_read_b128 v[154:157], v147 offset:1024
	ds_read_b128 v[158:161], v147 offset:2048
	ds_read_b128 v[162:165], v147 offset:3072
	ds_read_b128 v[166:169], v148
	ds_read_b128 v[170:173], v148 offset:1024
	ds_read_b128 v[174:177], v148 offset:2048
	ds_read_b128 v[178:181], v148 offset:3072
	s_add_u32 s24, s22, 0xfff80080
	s_addc_u32 s25, s23, -1
	s_cmp_eq_u32 s49, 28
	s_cselect_b32 s27, s15, s25
	s_cselect_b32 s26, s45, s24
	s_cselect_b32 s25, s13, s48
	s_cselect_b32 s24, s46, s47
	v_lshl_add_u64 v[190:191], s[22:23], 0, v[136:137]
	s_add_i32 m0, s21, 0xc000
	ds_read_b128 v[182:185], v149
	ds_read_b128 v[186:189], v149 offset:1024
	ds_read_b128 v[194:197], v149 offset:2048
	ds_read_b128 v[198:201], v149 offset:3072
	ds_read_b128 v[202:205], v149 offset:4096
	ds_read_b128 v[206:209], v149 offset:5120
	ds_read_b128 v[210:213], v149 offset:6144
	ds_read_b128 v[214:217], v149 offset:7168
	global_load_lds_dwordx4 v[190:191], off
	v_lshl_add_u64 v[190:191], s[22:23], 0, v[138:139]
	s_add_i32 m0, s21, 0xe000
	s_nop 0
	global_load_lds_dwordx4 v[190:191], off
	s_waitcnt vmcnt(8)
	s_waitcnt lgkmcnt(0)
	s_setprio 1
	s_barrier
	v_mfma_f32_16x16x32_bf16 v[124:127], v[150:153], v[182:185], v[124:127]
	v_mfma_f32_16x16x32_bf16 v[116:119], v[158:161], v[182:185], v[116:119]
	v_mfma_f32_16x16x32_bf16 v[108:111], v[150:153], v[194:197], v[108:111]
	v_mfma_f32_16x16x32_bf16 v[100:103], v[158:161], v[194:197], v[100:103]
	v_mfma_f32_16x16x32_bf16 v[92:95], v[150:153], v[202:205], v[92:95]
	v_mfma_f32_16x16x32_bf16 v[84:87], v[158:161], v[202:205], v[84:87]
	v_mfma_f32_16x16x32_bf16 v[76:79], v[150:153], v[210:213], v[76:79]
	v_mfma_f32_16x16x32_bf16 v[68:71], v[158:161], v[210:213], v[68:71]
	v_mfma_f32_16x16x32_bf16 v[124:127], v[154:157], v[186:189], v[124:127]
	v_mfma_f32_16x16x32_bf16 v[116:119], v[162:165], v[186:189], v[116:119]
	v_mfma_f32_16x16x32_bf16 v[108:111], v[154:157], v[198:201], v[108:111]
	v_mfma_f32_16x16x32_bf16 v[100:103], v[162:165], v[198:201], v[100:103]
	v_mfma_f32_16x16x32_bf16 v[92:95], v[154:157], v[206:209], v[92:95]
	v_mfma_f32_16x16x32_bf16 v[84:87], v[162:165], v[206:209], v[84:87]
	v_mfma_f32_16x16x32_bf16 v[76:79], v[154:157], v[214:217], v[76:79]
	v_mfma_f32_16x16x32_bf16 v[68:71], v[162:165], v[214:217], v[68:71]
	v_mfma_f32_16x16x32_bf16 v[120:123], v[166:169], v[182:185], v[120:123]
	v_mfma_f32_16x16x32_bf16 v[112:115], v[174:177], v[182:185], v[112:115]
	v_mfma_f32_16x16x32_bf16 v[104:107], v[166:169], v[194:197], v[104:107]
	v_mfma_f32_16x16x32_bf16 v[96:99], v[174:177], v[194:197], v[96:99]
	v_mfma_f32_16x16x32_bf16 v[88:91], v[166:169], v[202:205], v[88:91]
	v_mfma_f32_16x16x32_bf16 v[80:83], v[174:177], v[202:205], v[80:83]
	v_mfma_f32_16x16x32_bf16 v[72:75], v[166:169], v[210:213], v[72:75]
	v_mfma_f32_16x16x32_bf16 v[64:67], v[174:177], v[210:213], v[64:67]
	v_mfma_f32_16x16x32_bf16 v[120:123], v[170:173], v[186:189], v[120:123]
	v_mfma_f32_16x16x32_bf16 v[112:115], v[178:181], v[186:189], v[112:115]
	v_mfma_f32_16x16x32_bf16 v[104:107], v[170:173], v[198:201], v[104:107]
	v_mfma_f32_16x16x32_bf16 v[96:99], v[178:181], v[198:201], v[96:99]
	v_mfma_f32_16x16x32_bf16 v[88:91], v[170:173], v[206:209], v[88:91]
	v_mfma_f32_16x16x32_bf16 v[80:83], v[178:181], v[206:209], v[80:83]
	v_mfma_f32_16x16x32_bf16 v[72:75], v[170:173], v[214:217], v[72:75]
	v_mfma_f32_16x16x32_bf16 v[64:67], v[178:181], v[214:217], v[64:67]
	s_barrier
	s_setprio 0
	s_add_i32 s50, s42, s28
	v_lshl_add_u64 v[190:191], s[24:25], 0, v[130:131]
	s_mov_b32 m0, s50
	ds_read_b128 v[182:185], v149 offset:16384
	ds_read_b128 v[186:189], v149 offset:17408
	ds_read_b128 v[194:197], v149 offset:18432
	ds_read_b128 v[198:201], v149 offset:19456
	ds_read_b128 v[202:205], v149 offset:20480
	ds_read_b128 v[206:209], v149 offset:21504
	ds_read_b128 v[210:213], v149 offset:22528
	ds_read_b128 v[214:217], v149 offset:23552
	global_load_lds_dwordx4 v[190:191], off
	s_add_i32 m0, s50, 0x2000
	s_add_u32 s50, s24, 0x80000
	v_lshl_add_u64 v[218:219], s[24:25], 0, v[134:135]
	s_addc_u32 s51, s25, 0
	s_add_i32 s52, s43, s28
	global_load_lds_dwordx4 v[218:219], off
	v_lshl_add_u64 v[220:221], s[50:51], 0, v[130:131]
	s_mov_b32 m0, s52
	v_lshl_add_u64 v[222:223], s[26:27], 0, v[132:133]
	global_load_lds_dwordx4 v[220:221], off
	v_lshl_add_u64 v[220:221], s[50:51], 0, v[134:135]
	s_add_i32 m0, s52, 0x2000
	s_nop 0
	global_load_lds_dwordx4 v[220:221], off
	v_lshl_add_u64 v[220:221], s[26:27], 0, v[128:129]
	s_mov_b32 m0, s21
	s_nop 0
	global_load_lds_dwordx4 v[220:221], off
	s_mov_b32 m0, s31
	s_nop 0
	global_load_lds_dwordx4 v[222:223], off
	s_waitcnt vmcnt(8)
	s_waitcnt lgkmcnt(0)
	s_setprio 1
	s_barrier
; #define PG8_STAGE(bufoff, gbase, voff) do { _Pragma("unroll") for (int _i = 0; _i < 2; ++_i) \
;         __builtin_amdgcn_global_load_lds((const unsigned*)((const char*)(gbase) + (voff)[_i]), (LAS unsigned*)(lds + (bufoff) + ldsw + _i * 8192), 16, 0, 0); } while (0)
; #define PG8_LDA(dst, b, h) do { _Pragma("unroll") for (int m = 0; m < 4; ++m) _Pragma("unroll") for (int k = 0; k < 2; ++k) dst[m][k] = *(const LAS bf16x8*)(lds + PG8_SA(b, h) + aoff + m * 2048 + k * 1024); } while (0)
; #define PG8_LDB(dst, b, h) do { _Pragma("unroll") for (int n = 0; n < 2; ++n) _Pragma("unroll") for (int k = 0; k < 2; ++k) dst[n][k] = *(const LAS bf16x8*)(lds + PG8_SB(b, h) + boff + n * 2048 + k * 1024); } while (0)
; #define PG8_MMA(ai, bj, At, Bt) do { __builtin_amdgcn_s_setprio(1); _Pragma("unroll") for (int m = 0; m < 4; ++m) _Pragma("unroll") for (int n = 0; n < 2; ++n) _Pragma("unroll") for (int k = 0; k < 2; ++k) \
;         acc[ai][bj][m][n] = __builtin_amdgcn_mfma_f32_16x16x32_bf16(Bt[n][k], At[m][k], acc[ai][bj][m][n], 0, 0, 0); __builtin_amdgcn_s_setprio(0); } while (0)
; #define PG8_WAIT_V(n) asm volatile("s_waitcnt vmcnt(" #n ")" ::: "memory")
; #define PG8_WAIT_L(n) asm volatile("s_waitcnt lgkmcnt(" #n ")" ::: "memory")
; #define PG8_BAR __builtin_amdgcn_s_barrier()
; #define PG8_SCHED __builtin_amdgcn_sched_barrier(0)
; template <class Epi, class Sched = StaticOrder, class EpiSub = NoSub, bool FAST = false>
; __device__ __forceinline__ void gemm_phase(LAS unsigned char* lds, const Gemm g, const Sched& S, const Epi& E, const EpiSub& ES = EpiSub()) {
;     ...
;             PG8_WAIT_V(8); PG8_WAIT_L(0); PG8_BAR; PG8_MMA(1, 0, At, B0); PG8_MMA(1, 1, At, B1); PG8_BAR; PG8_SCHED;
;             PG8_LDB(B0, 1, 0); PG8_LDB(B1, 1, 1); PG8_SCHED; PG8_LDA(At, 1, 0); PG8_STAGE(PG8_SA(0, 1), a2 + hstepA, voffA);
;             PG8_WAIT_V(8); PG8_WAIT_L(0); PG8_BAR; PG8_MMA(0, 0, At, B0); PG8_MMA(0, 1, At, B1); PG8_BAR; PG8_SCHED;
	v_mfma_f32_16x16x32_bf16 v[60:63], v[150:153], v[182:185], v[60:63]
	v_mfma_f32_16x16x32_bf16 v[52:55], v[158:161], v[182:185], v[52:55]
	v_mfma_f32_16x16x32_bf16 v[44:47], v[150:153], v[194:197], v[44:47]
	v_mfma_f32_16x16x32_bf16 v[36:39], v[158:161], v[194:197], v[36:39]
	v_mfma_f32_16x16x32_bf16 v[28:31], v[150:153], v[202:205], v[28:31]
	v_mfma_f32_16x16x32_bf16 v[20:23], v[158:161], v[202:205], v[20:23]
	v_mfma_f32_16x16x32_bf16 v[12:15], v[150:153], v[210:213], v[12:15]
	v_mfma_f32_16x16x32_bf16 v[4:7], v[158:161], v[210:213], v[4:7]
	v_mfma_f32_16x16x32_bf16 v[60:63], v[154:157], v[186:189], v[60:63]
	v_mfma_f32_16x16x32_bf16 v[52:55], v[162:165], v[186:189], v[52:55]
	v_mfma_f32_16x16x32_bf16 v[44:47], v[154:157], v[198:201], v[44:47]
	v_mfma_f32_16x16x32_bf16 v[36:39], v[162:165], v[198:201], v[36:39]
	v_mfma_f32_16x16x32_bf16 v[28:31], v[154:157], v[206:209], v[28:31]
	v_mfma_f32_16x16x32_bf16 v[20:23], v[162:165], v[206:209], v[20:23]
	v_mfma_f32_16x16x32_bf16 v[12:15], v[154:157], v[214:217], v[12:15]
	v_mfma_f32_16x16x32_bf16 v[4:7], v[162:165], v[214:217], v[4:7]
	v_mfma_f32_16x16x32_bf16 v[56:59], v[166:169], v[182:185], v[56:59]
	v_mfma_f32_16x16x32_bf16 v[48:51], v[174:177], v[182:185], v[48:51]
	v_mfma_f32_16x16x32_bf16 v[40:43], v[166:169], v[194:197], v[40:43]
	v_mfma_f32_16x16x32_bf16 v[32:35], v[174:177], v[194:197], v[32:35]
	v_mfma_f32_16x16x32_bf16 v[24:27], v[166:169], v[202:205], v[24:27]
	v_mfma_f32_16x16x32_bf16 v[16:19], v[174:177], v[202:205], v[16:19]
	v_mfma_f32_16x16x32_bf16 v[8:11], v[166:169], v[210:213], v[8:11]
	v_mfma_f32_16x16x32_bf16 v[0:3], v[174:177], v[210:213], v[0:3]
	v_mfma_f32_16x16x32_bf16 v[56:59], v[170:173], v[186:189], v[56:59]
	v_mfma_f32_16x16x32_bf16 v[48:51], v[178:181], v[186:189], v[48:51]
	v_mfma_f32_16x16x32_bf16 v[40:43], v[170:173], v[198:201], v[40:43]
	v_mfma_f32_16x16x32_bf16 v[32:35], v[178:181], v[198:201], v[32:35]
	v_mfma_f32_16x16x32_bf16 v[24:27], v[170:173], v[206:209], v[24:27]
	v_mfma_f32_16x16x32_bf16 v[16:19], v[178:181], v[206:209], v[16:19]
	v_mfma_f32_16x16x32_bf16 v[8:11], v[170:173], v[214:217], v[8:11]
	v_mfma_f32_16x16x32_bf16 v[0:3], v[178:181], v[214:217], v[0:3]
	s_barrier
	s_setprio 0
	s_add_i32 s50, 0, 0x18000
	s_add_i32 s51, 0, 0x1c000
	v_add_u32_e32 v162, s50, v145
	v_add_u32_e32 v178, s51, v145
	ds_read_b128 v[150:153], v162
	ds_read_b128 v[154:157], v162 offset:1024
	ds_read_b128 v[158:161], v162 offset:2048
	ds_read_b128 v[162:165], v162 offset:3072
	ds_read_b128 v[166:169], v178
	ds_read_b128 v[170:173], v178 offset:1024
	ds_read_b128 v[174:177], v178 offset:2048
	ds_read_b128 v[178:181], v178 offset:3072
	s_add_u32 s26, s26, 0x80000
	s_addc_u32 s27, s27, 0
	s_mov_b32 m0, s36
	v_lshl_add_u64 v[224:225], s[26:27], 0, v[128:129]
	ds_read_b128 v[182:185], v149 offset:32768
	ds_read_b128 v[186:189], v149 offset:33792
	ds_read_b128 v[194:197], v149 offset:34816
	ds_read_b128 v[198:201], v149 offset:35840
	ds_read_b128 v[202:205], v149 offset:36864
	ds_read_b128 v[206:209], v149 offset:37888
	ds_read_b128 v[210:213], v149 offset:38912
	ds_read_b128 v[214:217], v149 offset:39936
	global_load_lds_dwordx4 v[224:225], off
	v_lshl_add_u64 v[224:225], s[26:27], 0, v[132:133]
	s_mov_b32 m0, s37
	s_nop 0
	global_load_lds_dwordx4 v[224:225], off
	s_waitcnt vmcnt(8)
	s_waitcnt lgkmcnt(0)
	s_setprio 1
	s_barrier
	v_mfma_f32_16x16x32_bf16 v[124:127], v[150:153], v[182:185], v[124:127]
	v_mfma_f32_16x16x32_bf16 v[116:119], v[158:161], v[182:185], v[116:119]
	v_mfma_f32_16x16x32_bf16 v[108:111], v[150:153], v[194:197], v[108:111]
	v_mfma_f32_16x16x32_bf16 v[100:103], v[158:161], v[194:197], v[100:103]
	v_mfma_f32_16x16x32_bf16 v[92:95], v[150:153], v[202:205], v[92:95]
	v_mfma_f32_16x16x32_bf16 v[84:87], v[158:161], v[202:205], v[84:87]
	v_mfma_f32_16x16x32_bf16 v[76:79], v[150:153], v[210:213], v[76:79]
	v_mfma_f32_16x16x32_bf16 v[68:71], v[158:161], v[210:213], v[68:71]
	v_mfma_f32_16x16x32_bf16 v[124:127], v[154:157], v[186:189], v[124:127]
	v_mfma_f32_16x16x32_bf16 v[116:119], v[162:165], v[186:189], v[116:119]
	v_mfma_f32_16x16x32_bf16 v[108:111], v[154:157], v[198:201], v[108:111]
	v_mfma_f32_16x16x32_bf16 v[100:103], v[162:165], v[198:201], v[100:103]
	v_mfma_f32_16x16x32_bf16 v[92:95], v[154:157], v[206:209], v[92:95]
	v_mfma_f32_16x16x32_bf16 v[84:87], v[162:165], v[206:209], v[84:87]
	v_mfma_f32_16x16x32_bf16 v[76:79], v[154:157], v[214:217], v[76:79]
	v_mfma_f32_16x16x32_bf16 v[68:71], v[162:165], v[214:217], v[68:71]
	v_mfma_f32_16x16x32_bf16 v[120:123], v[166:169], v[182:185], v[120:123]
	v_mfma_f32_16x16x32_bf16 v[112:115], v[174:177], v[182:185], v[112:115]
	v_mfma_f32_16x16x32_bf16 v[104:107], v[166:169], v[194:197], v[104:107]
	v_mfma_f32_16x16x32_bf16 v[96:99], v[174:177], v[194:197], v[96:99]
	v_mfma_f32_16x16x32_bf16 v[88:91], v[166:169], v[202:205], v[88:91]
	v_mfma_f32_16x16x32_bf16 v[80:83], v[174:177], v[202:205], v[80:83]
	v_mfma_f32_16x16x32_bf16 v[72:75], v[166:169], v[210:213], v[72:75]
	v_mfma_f32_16x16x32_bf16 v[64:67], v[174:177], v[210:213], v[64:67]
	v_mfma_f32_16x16x32_bf16 v[120:123], v[170:173], v[186:189], v[120:123]
	v_mfma_f32_16x16x32_bf16 v[112:115], v[178:181], v[186:189], v[112:115]
	v_mfma_f32_16x16x32_bf16 v[104:107], v[170:173], v[198:201], v[104:107]
	v_mfma_f32_16x16x32_bf16 v[96:99], v[178:181], v[198:201], v[96:99]
	v_mfma_f32_16x16x32_bf16 v[88:91], v[170:173], v[206:209], v[88:91]
	v_mfma_f32_16x16x32_bf16 v[80:83], v[178:181], v[206:209], v[80:83]
	v_mfma_f32_16x16x32_bf16 v[72:75], v[170:173], v[214:217], v[72:75]
	v_mfma_f32_16x16x32_bf16 v[64:67], v[178:181], v[214:217], v[64:67]
	s_barrier
; #define PG8_STAGE(bufoff, gbase, voff) do { _Pragma("unroll") for (int _i = 0; _i < 2; ++_i) \
;         __builtin_amdgcn_global_load_lds((const unsigned*)((const char*)(gbase) + (voff)[_i]), (LAS unsigned*)(lds + (bufoff) + ldsw + _i * 8192), 16, 0, 0); } while (0)
; #define PG8_LDA(dst, b, h) do { _Pragma("unroll") for (int m = 0; m < 4; ++m) _Pragma("unroll") for (int k = 0; k < 2; ++k) dst[m][k] = *(const LAS bf16x8*)(lds + PG8_SA(b, h) + aoff + m * 2048 + k * 1024); } while (0)
; #define PG8_MMA(ai, bj, At, Bt) do { __builtin_amdgcn_s_setprio(1); _Pragma("unroll") for (int m = 0; m < 4; ++m) _Pragma("unroll") for (int n = 0; n < 2; ++n) _Pragma("unroll") for (int k = 0; k < 2; ++k) \
;         acc[ai][bj][m][n] = __builtin_amdgcn_mfma_f32_16x16x32_bf16(Bt[n][k], At[m][k], acc[ai][bj][m][n], 0, 0, 0); __builtin_amdgcn_s_setprio(0); } while (0)
; #define PG8_WAIT_V(n) asm volatile("s_waitcnt vmcnt(" #n ")" ::: "memory")
; #define PG8_WAIT_L(n) asm volatile("s_waitcnt lgkmcnt(" #n ")" ::: "memory")
; #define PG8_BAR __builtin_amdgcn_s_barrier()
; #define PG8_SCHED __builtin_amdgcn_sched_barrier(0)
; template <class Epi, class Sched = StaticOrder, class EpiSub = NoSub, bool FAST = false>
; __device__ __forceinline__ void gemm_phase(LAS unsigned char* lds, const Gemm g, const Sched& S, const Epi& E, const EpiSub& ES = EpiSub()) {
;     ...
;         for (int t = 0; t < nt; t += 2) {
;     ...
;             PG8_LDA(At, 1, 1); PG8_STAGE(PG8_SB(1, 0), b3, voffB); PG8_STAGE(PG8_SB(1, 1), b3 + hstepB, voffB); PG8_STAGE(PG8_SA(1, 0), a3, voffA);
;             PG8_WAIT_V(8); PG8_WAIT_L(0); PG8_BAR; PG8_MMA(1, 0, At, B0); PG8_MMA(1, 1, At, B1); PG8_BAR; PG8_SCHED;
	s_setprio 0
	s_add_i32 s26, s50, s28
	v_lshl_add_u64 v[190:191], v[190:191], 0, s[8:9]
	s_mov_b32 m0, s26
	ds_read_b128 v[182:185], v149 offset:49152
	ds_read_b128 v[186:189], v149 offset:50176
	ds_read_b128 v[194:197], v149 offset:51200
	ds_read_b128 v[198:201], v149 offset:52224
	ds_read_b128 v[202:205], v149 offset:53248
	ds_read_b128 v[206:209], v149 offset:54272
	ds_read_b128 v[210:213], v149 offset:55296
	ds_read_b128 v[214:217], v149 offset:56320
	global_load_lds_dwordx4 v[190:191], off
	s_add_i32 m0, s26, 0x2000
	s_add_u32 s24, s24, 0x80080
	v_lshl_add_u64 v[190:191], v[218:219], 0, s[8:9]
	s_addc_u32 s25, s25, 0
	s_add_i32 s26, s51, s28
	global_load_lds_dwordx4 v[190:191], off
	v_lshl_add_u64 v[190:191], s[24:25], 0, v[130:131]
	s_mov_b32 m0, s26
	s_nop 0
	global_load_lds_dwordx4 v[190:191], off
	v_lshl_add_u64 v[190:191], s[24:25], 0, v[134:135]
	s_add_i32 m0, s26, 0x2000
	s_nop 0
	global_load_lds_dwordx4 v[190:191], off
	v_lshl_add_u64 v[190:191], v[220:221], 0, s[8:9]
	s_mov_b32 m0, s40
	s_nop 0
	global_load_lds_dwordx4 v[190:191], off
	v_lshl_add_u64 v[190:191], v[222:223], 0, s[8:9]
	s_mov_b32 m0, s41
	s_nop 0
	global_load_lds_dwordx4 v[190:191], off
	s_waitcnt vmcnt(8)
	s_waitcnt lgkmcnt(0)
	s_setprio 1
	s_barrier
	v_mfma_f32_16x16x32_bf16 v[60:63], v[150:153], v[182:185], v[60:63]
	v_mfma_f32_16x16x32_bf16 v[52:55], v[158:161], v[182:185], v[52:55]
	v_mfma_f32_16x16x32_bf16 v[44:47], v[150:153], v[194:197], v[44:47]
	v_mfma_f32_16x16x32_bf16 v[36:39], v[158:161], v[194:197], v[36:39]
	v_mfma_f32_16x16x32_bf16 v[28:31], v[150:153], v[202:205], v[28:31]
	v_mfma_f32_16x16x32_bf16 v[20:23], v[158:161], v[202:205], v[20:23]
	v_mfma_f32_16x16x32_bf16 v[12:15], v[150:153], v[210:213], v[12:15]
	v_mfma_f32_16x16x32_bf16 v[4:7], v[158:161], v[210:213], v[4:7]
	v_mfma_f32_16x16x32_bf16 v[60:63], v[154:157], v[186:189], v[60:63]
	v_mfma_f32_16x16x32_bf16 v[52:55], v[162:165], v[186:189], v[52:55]
	v_mfma_f32_16x16x32_bf16 v[44:47], v[154:157], v[198:201], v[44:47]
	v_mfma_f32_16x16x32_bf16 v[36:39], v[162:165], v[198:201], v[36:39]
	v_mfma_f32_16x16x32_bf16 v[28:31], v[154:157], v[206:209], v[28:31]
	v_mfma_f32_16x16x32_bf16 v[20:23], v[162:165], v[206:209], v[20:23]
	v_mfma_f32_16x16x32_bf16 v[12:15], v[154:157], v[214:217], v[12:15]
	v_mfma_f32_16x16x32_bf16 v[4:7], v[162:165], v[214:217], v[4:7]
	v_mfma_f32_16x16x32_bf16 v[56:59], v[166:169], v[182:185], v[56:59]
	v_mfma_f32_16x16x32_bf16 v[48:51], v[174:177], v[182:185], v[48:51]
	v_mfma_f32_16x16x32_bf16 v[40:43], v[166:169], v[194:197], v[40:43]
	v_mfma_f32_16x16x32_bf16 v[32:35], v[174:177], v[194:197], v[32:35]
	v_mfma_f32_16x16x32_bf16 v[24:27], v[166:169], v[202:205], v[24:27]
	v_mfma_f32_16x16x32_bf16 v[16:19], v[174:177], v[202:205], v[16:19]
	v_mfma_f32_16x16x32_bf16 v[8:11], v[166:169], v[210:213], v[8:11]
	v_mfma_f32_16x16x32_bf16 v[0:3], v[174:177], v[210:213], v[0:3]
	v_mfma_f32_16x16x32_bf16 v[56:59], v[170:173], v[186:189], v[56:59]
	v_mfma_f32_16x16x32_bf16 v[48:51], v[178:181], v[186:189], v[48:51]
	v_mfma_f32_16x16x32_bf16 v[40:43], v[170:173], v[198:201], v[40:43]
	v_mfma_f32_16x16x32_bf16 v[32:35], v[178:181], v[198:201], v[32:35]
	v_mfma_f32_16x16x32_bf16 v[24:27], v[170:173], v[206:209], v[24:27]
	v_mfma_f32_16x16x32_bf16 v[16:19], v[178:181], v[206:209], v[16:19]
	v_mfma_f32_16x16x32_bf16 v[8:11], v[170:173], v[214:217], v[8:11]
	v_mfma_f32_16x16x32_bf16 v[0:3], v[178:181], v[214:217], v[0:3]
	s_barrier
	s_setprio 0
	s_add_i32 s49, s49, 2
	s_add_u32 s22, s22, 0x100
	s_addc_u32 s23, s23, 0
	s_add_u32 s47, s47, 0x100
	s_addc_u32 s48, s48, 0
	s_cmp_gt_u32 s49, 29
	s_cbranch_scc0 .LBB0_985
	s_and_b64 vcc, exec, s[10:11]
	s_cbranch_vccz .LBB0_988
	s_barrier

; #define PG8_STAGE(bufoff, gbase, voff) do { _Pragma("unroll") for (int _i = 0; _i < 2; ++_i) \
;         __builtin_amdgcn_global_load_lds((const unsigned*)((const char*)(gbase) + (voff)[_i]), (LAS unsigned*)(lds + (bufoff) + ldsw + _i * 8192), 16, 0, 0); } while (0)
; #define PG8_LDA(dst, b, h) do { _Pragma("unroll") for (int m = 0; m < 4; ++m) _Pragma("unroll") for (int k = 0; k < 2; ++k) dst[m][k] = *(const LAS bf16x8*)(lds + PG8_SA(b, h) + aoff + m * 2048 + k * 1024); } while (0)
; #define PG8_LDB(dst, b, h) do { _Pragma("unroll") for (int n = 0; n < 2; ++n) _Pragma("unroll") for (int k = 0; k < 2; ++k) dst[n][k] = *(const LAS bf16x8*)(lds + PG8_SB(b, h) + boff + n * 2048 + k * 1024); } while (0)
; #define PG8_MMA(ai, bj, At, Bt) do { __builtin_amdgcn_s_setprio(1); _Pragma("unroll") for (int m = 0; m < 4; ++m) _Pragma("unroll") for (int n = 0; n < 2; ++n) _Pragma("unroll") for (int k = 0; k < 2; ++k) \
;         acc[ai][bj][m][n] = __builtin_amdgcn_mfma_f32_16x16x32_bf16(Bt[n][k], At[m][k], acc[ai][bj][m][n], 0, 0, 0); __builtin_amdgcn_s_setprio(0); } while (0)
; #define PG8_WAIT_V(n) asm volatile("s_waitcnt vmcnt(" #n ")" ::: "memory")
; #define PG8_WAIT_L(n) asm volatile("s_waitcnt lgkmcnt(" #n ")" ::: "memory")
; #define PG8_BAR __builtin_amdgcn_s_barrier()
; template <class Epi, class Sched = StaticOrder, class EpiSub = NoSub, bool FAST = false>
; __device__ __forceinline__ void gemm_phase(LAS unsigned char* lds, const Gemm g, const Sched& S, const Epi& E, const EpiSub& ES = EpiSub()) {
;     ...
;             const bool last = (t == nt - 2);
;             const char* a1 = cA + (size_t)(t + 1) * kstep;
;             const char* a2 = last ? nA : cA + (size_t)(t + 2) * kstep; const char* b2 = last ? nB : cB + (size_t)(t + 2) * kstep;
;             const char* a3 = a2 + kstep; const char* b3 = b2 + kstep;
;             if constexpr (FAST && PG8_SP2) {
;             PG8_LDB(B0, 0, 0); PG8_LDB(B1, 0, 1); PG8_SCHED; PG8_LDA(At, 0, 0); PG8_STAGE(PG8_SA(1, 1), a1 + hstepA, voffA);
;             PG8_WAIT_V(8); PG8_WAIT_L(0); PG8_BAR; PG8_MMA(0, 0, At, B0); PG8_MMA(0, 1, At, B1); PG8_BAR; PG8_SCHED;
;             PG8_LDA(At, 0, 1); PG8_STAGE(PG8_SB(0, 0), b2, voffB); PG8_STAGE(PG8_SB(0, 1), b2 + hstepB, voffB); PG8_STAGE(PG8_SA(0, 0), a2, voffA);
;             PG8_WAIT_V(8); PG8_WAIT_L(0); PG8_BAR; PG8_MMA(1, 0, At, B0); PG8_MMA(1, 1, At, B1); PG8_BAR; PG8_SCHED;
.LBB0_1079:
	ds_read_b128 v[96:99], v201
	ds_read_b128 v[100:103], v201 offset:1024
	ds_read_b128 v[108:111], v201 offset:2048
	ds_read_b128 v[116:119], v201 offset:3072
	ds_read_b128 v[144:147], v202
	ds_read_b128 v[148:151], v202 offset:1024
	ds_read_b128 v[152:155], v202 offset:2048
	ds_read_b128 v[156:159], v202 offset:3072
	s_add_i32 s85, s46, 2
	s_add_u32 s44, s42, 0xffea0080
	s_addc_u32 s45, s43, -1
	s_cmp_eq_u32 s71, s46
	s_cselect_b32 s46, s38, s44
	s_cselect_b32 s47, s39, s45
	s_cselect_b32 s45, s41, s84
	s_cselect_b32 s44, s40, s83
	v_lshl_add_u64 v[190:191], s[42:43], 0, v[176:177]
	s_add_i32 m0, s48, 0xc000
	ds_read_b128 v[160:163], v203
	ds_read_b128 v[164:167], v203 offset:1024
	ds_read_b128 v[182:185], v203 offset:2048
	ds_read_b128 v[186:189], v203 offset:3072
	ds_read_b128 v[194:197], v203 offset:4096
	ds_read_b128 v[204:207], v203 offset:5120
	ds_read_b128 v[208:211], v203 offset:6144
	ds_read_b128 v[212:215], v203 offset:7168
	global_load_lds_dwordx4 v[190:191], off
	v_lshl_add_u64 v[190:191], s[42:43], 0, v[178:179]
	s_add_i32 m0, s48, 0xe000
	s_nop 0
	global_load_lds_dwordx4 v[190:191], off
	s_waitcnt vmcnt(8)
	s_waitcnt lgkmcnt(0)
	s_setprio 1
	s_barrier
	v_mfma_f32_16x16x32_bf16 v[140:143], v[96:99], v[160:163], v[140:143]
	v_mfma_f32_16x16x32_bf16 v[136:139], v[108:111], v[160:163], v[136:139]
	v_mfma_f32_16x16x32_bf16 v[124:127], v[96:99], v[182:185], v[124:127]
	v_mfma_f32_16x16x32_bf16 v[120:123], v[108:111], v[182:185], v[120:123]
	v_mfma_f32_16x16x32_bf16 v[92:95], v[96:99], v[194:197], v[92:95]
	v_mfma_f32_16x16x32_bf16 v[88:91], v[108:111], v[194:197], v[88:91]
	v_mfma_f32_16x16x32_bf16 v[76:79], v[96:99], v[208:211], v[76:79]
	v_mfma_f32_16x16x32_bf16 v[72:75], v[108:111], v[208:211], v[72:75]
	v_mfma_f32_16x16x32_bf16 v[140:143], v[100:103], v[164:167], v[140:143]
	v_mfma_f32_16x16x32_bf16 v[136:139], v[116:119], v[164:167], v[136:139]
	v_mfma_f32_16x16x32_bf16 v[124:127], v[100:103], v[186:189], v[124:127]
	v_mfma_f32_16x16x32_bf16 v[120:123], v[116:119], v[186:189], v[120:123]
	v_mfma_f32_16x16x32_bf16 v[92:95], v[100:103], v[204:207], v[92:95]
	v_mfma_f32_16x16x32_bf16 v[88:91], v[116:119], v[204:207], v[88:91]
	v_mfma_f32_16x16x32_bf16 v[76:79], v[100:103], v[212:215], v[76:79]
	v_mfma_f32_16x16x32_bf16 v[72:75], v[116:119], v[212:215], v[72:75]
	v_mfma_f32_16x16x32_bf16 v[132:135], v[144:147], v[160:163], v[132:135]
	v_mfma_f32_16x16x32_bf16 v[128:131], v[152:155], v[160:163], v[128:131]
	v_mfma_f32_16x16x32_bf16 v[112:115], v[144:147], v[182:185], v[112:115]
	v_mfma_f32_16x16x32_bf16 v[104:107], v[152:155], v[182:185], v[104:107]
	v_mfma_f32_16x16x32_bf16 v[84:87], v[144:147], v[194:197], v[84:87]
	v_mfma_f32_16x16x32_bf16 v[80:83], v[152:155], v[194:197], v[80:83]
	v_mfma_f32_16x16x32_bf16 v[68:71], v[144:147], v[208:211], v[68:71]
	v_mfma_f32_16x16x32_bf16 v[64:67], v[152:155], v[208:211], v[64:67]
	v_mfma_f32_16x16x32_bf16 v[132:135], v[148:151], v[164:167], v[132:135]
	v_mfma_f32_16x16x32_bf16 v[128:131], v[156:159], v[164:167], v[128:131]
	v_mfma_f32_16x16x32_bf16 v[112:115], v[148:151], v[186:189], v[112:115]
	v_mfma_f32_16x16x32_bf16 v[104:107], v[156:159], v[186:189], v[104:107]
	v_mfma_f32_16x16x32_bf16 v[84:87], v[148:151], v[204:207], v[84:87]
	v_mfma_f32_16x16x32_bf16 v[80:83], v[156:159], v[204:207], v[80:83]
	v_mfma_f32_16x16x32_bf16 v[68:71], v[148:151], v[212:215], v[68:71]
	v_mfma_f32_16x16x32_bf16 v[64:67], v[156:159], v[212:215], v[64:67]
	s_barrier
	s_setprio 0
	s_add_i32 s86, s58, s27
	v_lshl_add_u64 v[190:191], s[44:45], 0, v[170:171]
	s_mov_b32 m0, s86
	ds_read_b128 v[160:163], v203 offset:16384
	ds_read_b128 v[164:167], v203 offset:17408
	ds_read_b128 v[182:185], v203 offset:18432
	ds_read_b128 v[186:189], v203 offset:19456
	ds_read_b128 v[194:197], v203 offset:20480
	ds_read_b128 v[204:207], v203 offset:21504
	ds_read_b128 v[208:211], v203 offset:22528
	ds_read_b128 v[212:215], v203 offset:23552
	global_load_lds_dwordx4 v[190:191], off
	s_add_i32 m0, s86, 0x2000
	s_add_u32 s86, s44, 0x160000
	v_lshl_add_u64 v[216:217], s[44:45], 0, v[174:175]
	s_addc_u32 s87, s45, 0
	s_add_i32 s88, s59, s27
	global_load_lds_dwordx4 v[216:217], off
	v_lshl_add_u64 v[218:219], s[86:87], 0, v[170:171]
	s_mov_b32 m0, s88
	v_lshl_add_u64 v[220:221], s[46:47], 0, v[172:173]
	global_load_lds_dwordx4 v[218:219], off
	v_lshl_add_u64 v[218:219], s[86:87], 0, v[174:175]
	s_add_i32 m0, s88, 0x2000
	s_nop 0
	global_load_lds_dwordx4 v[218:219], off
	v_lshl_add_u64 v[218:219], s[46:47], 0, v[168:169]
	s_mov_b32 m0, s48
	s_nop 0
	global_load_lds_dwordx4 v[218:219], off
	s_mov_b32 m0, s49
	s_nop 0
	global_load_lds_dwordx4 v[220:221], off
	s_waitcnt vmcnt(8)
	s_waitcnt lgkmcnt(0)
	s_setprio 1
	s_barrier
; #define PG8_STAGE(bufoff, gbase, voff) do { _Pragma("unroll") for (int _i = 0; _i < 2; ++_i) \
;         __builtin_amdgcn_global_load_lds((const unsigned*)((const char*)(gbase) + (voff)[_i]), (LAS unsigned*)(lds + (bufoff) + ldsw + _i * 8192), 16, 0, 0); } while (0)
; #define PG8_LDA(dst, b, h) do { _Pragma("unroll") for (int m = 0; m < 4; ++m) _Pragma("unroll") for (int k = 0; k < 2; ++k) dst[m][k] = *(const LAS bf16x8*)(lds + PG8_SA(b, h) + aoff + m * 2048 + k * 1024); } while (0)
; #define PG8_LDB(dst, b, h) do { _Pragma("unroll") for (int n = 0; n < 2; ++n) _Pragma("unroll") for (int k = 0; k < 2; ++k) dst[n][k] = *(const LAS bf16x8*)(lds + PG8_SB(b, h) + boff + n * 2048 + k * 1024); } while (0)
; #define PG8_MMA(ai, bj, At, Bt) do { __builtin_amdgcn_s_setprio(1); _Pragma("unroll") for (int m = 0; m < 4; ++m) _Pragma("unroll") for (int n = 0; n < 2; ++n) _Pragma("unroll") for (int k = 0; k < 2; ++k) \
;         acc[ai][bj][m][n] = __builtin_amdgcn_mfma_f32_16x16x32_bf16(Bt[n][k], At[m][k], acc[ai][bj][m][n], 0, 0, 0); __builtin_amdgcn_s_setprio(0); } while (0)
; #define PG8_WAIT_V(n) asm volatile("s_waitcnt vmcnt(" #n ")" ::: "memory")
; #define PG8_WAIT_L(n) asm volatile("s_waitcnt lgkmcnt(" #n ")" ::: "memory")
; #define PG8_BAR __builtin_amdgcn_s_barrier()
; #define PG8_SCHED __builtin_amdgcn_sched_barrier(0)
; template <class Epi, class Sched = StaticOrder, class EpiSub = NoSub, bool FAST = false>
; __device__ __forceinline__ void gemm_phase(LAS unsigned char* lds, const Gemm g, const Sched& S, const Epi& E, const EpiSub& ES = EpiSub()) {
;     ...
;             PG8_WAIT_V(8); PG8_WAIT_L(0); PG8_BAR; PG8_MMA(1, 0, At, B0); PG8_MMA(1, 1, At, B1); PG8_BAR; PG8_SCHED;
;             PG8_LDB(B0, 1, 0); PG8_LDB(B1, 1, 1); PG8_SCHED; PG8_LDA(At, 1, 0); PG8_STAGE(PG8_SA(0, 1), a2 + hstepA, voffA);
;             PG8_WAIT_V(8); PG8_WAIT_L(0); PG8_BAR; PG8_MMA(0, 0, At, B0); PG8_MMA(0, 1, At, B1); PG8_BAR; PG8_SCHED;
	v_mfma_f32_16x16x32_bf16 v[60:63], v[96:99], v[160:163], v[60:63]
	v_mfma_f32_16x16x32_bf16 v[56:59], v[108:111], v[160:163], v[56:59]
	v_mfma_f32_16x16x32_bf16 v[44:47], v[96:99], v[182:185], v[44:47]
	v_mfma_f32_16x16x32_bf16 v[40:43], v[108:111], v[182:185], v[40:43]
	v_mfma_f32_16x16x32_bf16 v[28:31], v[96:99], v[194:197], v[28:31]
	v_mfma_f32_16x16x32_bf16 v[24:27], v[108:111], v[194:197], v[24:27]
	v_mfma_f32_16x16x32_bf16 v[12:15], v[96:99], v[208:211], v[12:15]
	v_mfma_f32_16x16x32_bf16 v[8:11], v[108:111], v[208:211], v[8:11]
	v_mfma_f32_16x16x32_bf16 v[60:63], v[100:103], v[164:167], v[60:63]
	v_mfma_f32_16x16x32_bf16 v[56:59], v[116:119], v[164:167], v[56:59]
	v_mfma_f32_16x16x32_bf16 v[44:47], v[100:103], v[186:189], v[44:47]
	v_mfma_f32_16x16x32_bf16 v[40:43], v[116:119], v[186:189], v[40:43]
	v_mfma_f32_16x16x32_bf16 v[28:31], v[100:103], v[204:207], v[28:31]
	v_mfma_f32_16x16x32_bf16 v[24:27], v[116:119], v[204:207], v[24:27]
	v_mfma_f32_16x16x32_bf16 v[12:15], v[100:103], v[212:215], v[12:15]
	v_mfma_f32_16x16x32_bf16 v[8:11], v[116:119], v[212:215], v[8:11]
	v_mfma_f32_16x16x32_bf16 v[52:55], v[144:147], v[160:163], v[52:55]
	v_mfma_f32_16x16x32_bf16 v[48:51], v[152:155], v[160:163], v[48:51]
	v_mfma_f32_16x16x32_bf16 v[36:39], v[144:147], v[182:185], v[36:39]
	v_mfma_f32_16x16x32_bf16 v[32:35], v[152:155], v[182:185], v[32:35]
	v_mfma_f32_16x16x32_bf16 v[20:23], v[144:147], v[194:197], v[20:23]
	v_mfma_f32_16x16x32_bf16 v[16:19], v[152:155], v[194:197], v[16:19]
	v_mfma_f32_16x16x32_bf16 v[4:7], v[144:147], v[208:211], v[4:7]
	v_mfma_f32_16x16x32_bf16 v[0:3], v[152:155], v[208:211], v[0:3]
	v_mfma_f32_16x16x32_bf16 v[52:55], v[148:151], v[164:167], v[52:55]
	v_mfma_f32_16x16x32_bf16 v[48:51], v[156:159], v[164:167], v[48:51]
	v_mfma_f32_16x16x32_bf16 v[36:39], v[148:151], v[186:189], v[36:39]
	v_mfma_f32_16x16x32_bf16 v[32:35], v[156:159], v[186:189], v[32:35]
	v_mfma_f32_16x16x32_bf16 v[20:23], v[148:151], v[204:207], v[20:23]
	v_mfma_f32_16x16x32_bf16 v[16:19], v[156:159], v[204:207], v[16:19]
	v_mfma_f32_16x16x32_bf16 v[4:7], v[148:151], v[212:215], v[4:7]
	v_mfma_f32_16x16x32_bf16 v[0:3], v[156:159], v[212:215], v[0:3]
	s_barrier
	s_setprio 0
	s_add_i32 s86, 0, 0x18000
	s_add_i32 s87, 0, 0x1c000
	v_add_u32_e32 v116, s86, v198
	v_add_u32_e32 v156, s87, v198
	ds_read_b128 v[96:99], v116
	ds_read_b128 v[100:103], v116 offset:1024
	ds_read_b128 v[108:111], v116 offset:2048
	ds_read_b128 v[116:119], v116 offset:3072
	ds_read_b128 v[144:147], v156
	ds_read_b128 v[148:151], v156 offset:1024
	ds_read_b128 v[152:155], v156 offset:2048
	ds_read_b128 v[156:159], v156 offset:3072
	s_add_u32 s46, s46, 0x160000
	s_addc_u32 s47, s47, 0
	s_mov_b32 m0, s50
	v_lshl_add_u64 v[222:223], s[46:47], 0, v[168:169]
	ds_read_b128 v[160:163], v203 offset:32768
	ds_read_b128 v[164:167], v203 offset:33792
	ds_read_b128 v[182:185], v203 offset:34816
	ds_read_b128 v[186:189], v203 offset:35840
	ds_read_b128 v[194:197], v203 offset:36864
	ds_read_b128 v[204:207], v203 offset:37888
	ds_read_b128 v[208:211], v203 offset:38912
	ds_read_b128 v[212:215], v203 offset:39936
	global_load_lds_dwordx4 v[222:223], off
	v_lshl_add_u64 v[222:223], s[46:47], 0, v[172:173]
	s_mov_b32 m0, s51
	s_nop 0
	global_load_lds_dwordx4 v[222:223], off
	s_waitcnt vmcnt(8)
	s_waitcnt lgkmcnt(0)
	s_setprio 1
	s_barrier
	v_mfma_f32_16x16x32_bf16 v[140:143], v[96:99], v[160:163], v[140:143]
	v_mfma_f32_16x16x32_bf16 v[136:139], v[108:111], v[160:163], v[136:139]
	v_mfma_f32_16x16x32_bf16 v[124:127], v[96:99], v[182:185], v[124:127]
	v_mfma_f32_16x16x32_bf16 v[120:123], v[108:111], v[182:185], v[120:123]
	v_mfma_f32_16x16x32_bf16 v[92:95], v[96:99], v[194:197], v[92:95]
	v_mfma_f32_16x16x32_bf16 v[88:91], v[108:111], v[194:197], v[88:91]
	v_mfma_f32_16x16x32_bf16 v[76:79], v[96:99], v[208:211], v[76:79]
	v_mfma_f32_16x16x32_bf16 v[72:75], v[108:111], v[208:211], v[72:75]
	v_mfma_f32_16x16x32_bf16 v[140:143], v[100:103], v[164:167], v[140:143]
	v_mfma_f32_16x16x32_bf16 v[136:139], v[116:119], v[164:167], v[136:139]
	v_mfma_f32_16x16x32_bf16 v[124:127], v[100:103], v[186:189], v[124:127]
	v_mfma_f32_16x16x32_bf16 v[120:123], v[116:119], v[186:189], v[120:123]
	v_mfma_f32_16x16x32_bf16 v[92:95], v[100:103], v[204:207], v[92:95]
	v_mfma_f32_16x16x32_bf16 v[88:91], v[116:119], v[204:207], v[88:91]
	v_mfma_f32_16x16x32_bf16 v[76:79], v[100:103], v[212:215], v[76:79]
	v_mfma_f32_16x16x32_bf16 v[72:75], v[116:119], v[212:215], v[72:75]
	v_mfma_f32_16x16x32_bf16 v[132:135], v[144:147], v[160:163], v[132:135]
	v_mfma_f32_16x16x32_bf16 v[128:131], v[152:155], v[160:163], v[128:131]
	v_mfma_f32_16x16x32_bf16 v[112:115], v[144:147], v[182:185], v[112:115]
	v_mfma_f32_16x16x32_bf16 v[104:107], v[152:155], v[182:185], v[104:107]
	v_mfma_f32_16x16x32_bf16 v[84:87], v[144:147], v[194:197], v[84:87]
	v_mfma_f32_16x16x32_bf16 v[80:83], v[152:155], v[194:197], v[80:83]
	v_mfma_f32_16x16x32_bf16 v[68:71], v[144:147], v[208:211], v[68:71]
	v_mfma_f32_16x16x32_bf16 v[64:67], v[152:155], v[208:211], v[64:67]
	v_mfma_f32_16x16x32_bf16 v[132:135], v[148:151], v[164:167], v[132:135]
	v_mfma_f32_16x16x32_bf16 v[128:131], v[156:159], v[164:167], v[128:131]
	v_mfma_f32_16x16x32_bf16 v[112:115], v[148:151], v[186:189], v[112:115]
	v_mfma_f32_16x16x32_bf16 v[104:107], v[156:159], v[186:189], v[104:107]
	v_mfma_f32_16x16x32_bf16 v[84:87], v[148:151], v[204:207], v[84:87]
	v_mfma_f32_16x16x32_bf16 v[80:83], v[156:159], v[204:207], v[80:83]
	v_mfma_f32_16x16x32_bf16 v[68:71], v[148:151], v[212:215], v[68:71]
	v_mfma_f32_16x16x32_bf16 v[64:67], v[156:159], v[212:215], v[64:67]
	s_barrier
; #define PG8_STAGE(bufoff, gbase, voff) do { _Pragma("unroll") for (int _i = 0; _i < 2; ++_i) \
;         __builtin_amdgcn_global_load_lds((const unsigned*)((const char*)(gbase) + (voff)[_i]), (LAS unsigned*)(lds + (bufoff) + ldsw + _i * 8192), 16, 0, 0); } while (0)
; #define PG8_LDA(dst, b, h) do { _Pragma("unroll") for (int m = 0; m < 4; ++m) _Pragma("unroll") for (int k = 0; k < 2; ++k) dst[m][k] = *(const LAS bf16x8*)(lds + PG8_SA(b, h) + aoff + m * 2048 + k * 1024); } while (0)
; #define PG8_MMA(ai, bj, At, Bt) do { __builtin_amdgcn_s_setprio(1); _Pragma("unroll") for (int m = 0; m < 4; ++m) _Pragma("unroll") for (int n = 0; n < 2; ++n) _Pragma("unroll") for (int k = 0; k < 2; ++k) \
;         acc[ai][bj][m][n] = __builtin_amdgcn_mfma_f32_16x16x32_bf16(Bt[n][k], At[m][k], acc[ai][bj][m][n], 0, 0, 0); __builtin_amdgcn_s_setprio(0); } while (0)
; #define PG8_WAIT_V(n) asm volatile("s_waitcnt vmcnt(" #n ")" ::: "memory")
; #define PG8_WAIT_L(n) asm volatile("s_waitcnt lgkmcnt(" #n ")" ::: "memory")
; #define PG8_BAR __builtin_amdgcn_s_barrier()
; #define PG8_SCHED __builtin_amdgcn_sched_barrier(0)
; template <class Epi, class Sched = StaticOrder, class EpiSub = NoSub, bool FAST = false>
; __device__ __forceinline__ void gemm_phase(LAS unsigned char* lds, const Gemm g, const Sched& S, const Epi& E, const EpiSub& ES = EpiSub()) {
;     ...
;         for (int t = 0; t < nt; t += 2) {
;     ...
;             PG8_LDA(At, 1, 1); PG8_STAGE(PG8_SB(1, 0), b3, voffB); PG8_STAGE(PG8_SB(1, 1), b3 + hstepB, voffB); PG8_STAGE(PG8_SA(1, 0), a3, voffA);
;             PG8_WAIT_V(8); PG8_WAIT_L(0); PG8_BAR; PG8_MMA(1, 0, At, B0); PG8_MMA(1, 1, At, B1); PG8_BAR; PG8_SCHED;
	s_setprio 0
	s_add_i32 s46, s86, s27
	v_lshl_add_u64 v[190:191], v[190:191], 0, s[16:17]
	s_mov_b32 m0, s46
	ds_read_b128 v[160:163], v203 offset:49152
	ds_read_b128 v[164:167], v203 offset:50176
	ds_read_b128 v[182:185], v203 offset:51200
	ds_read_b128 v[186:189], v203 offset:52224
	ds_read_b128 v[194:197], v203 offset:53248
	ds_read_b128 v[204:207], v203 offset:54272
	ds_read_b128 v[208:211], v203 offset:55296
	ds_read_b128 v[212:215], v203 offset:56320
	global_load_lds_dwordx4 v[190:191], off
	s_add_i32 m0, s46, 0x2000
	s_add_u32 s44, s44, 0x160080
	v_lshl_add_u64 v[190:191], v[216:217], 0, s[16:17]
	s_addc_u32 s45, s45, 0
	s_add_i32 s46, s87, s27
	global_load_lds_dwordx4 v[190:191], off
	v_lshl_add_u64 v[190:191], s[44:45], 0, v[170:171]
	s_mov_b32 m0, s46
	s_nop 0
	global_load_lds_dwordx4 v[190:191], off
	v_lshl_add_u64 v[190:191], s[44:45], 0, v[174:175]
	s_add_i32 m0, s46, 0x2000
	s_nop 0
	global_load_lds_dwordx4 v[190:191], off
	v_lshl_add_u64 v[190:191], v[218:219], 0, s[16:17]
	s_mov_b32 m0, s53
	s_nop 0
	global_load_lds_dwordx4 v[190:191], off
	v_lshl_add_u64 v[190:191], v[220:221], 0, s[16:17]
	s_mov_b32 m0, s54
	s_nop 0
	global_load_lds_dwordx4 v[190:191], off
	s_waitcnt vmcnt(8)
	s_waitcnt lgkmcnt(0)
	s_setprio 1
	s_barrier
	v_mfma_f32_16x16x32_bf16 v[60:63], v[96:99], v[160:163], v[60:63]
	v_mfma_f32_16x16x32_bf16 v[56:59], v[108:111], v[160:163], v[56:59]
	v_mfma_f32_16x16x32_bf16 v[44:47], v[96:99], v[182:185], v[44:47]
	v_mfma_f32_16x16x32_bf16 v[40:43], v[108:111], v[182:185], v[40:43]
	v_mfma_f32_16x16x32_bf16 v[28:31], v[96:99], v[194:197], v[28:31]
	v_mfma_f32_16x16x32_bf16 v[24:27], v[108:111], v[194:197], v[24:27]
	v_mfma_f32_16x16x32_bf16 v[12:15], v[96:99], v[208:211], v[12:15]
	v_mfma_f32_16x16x32_bf16 v[8:11], v[108:111], v[208:211], v[8:11]
	v_mfma_f32_16x16x32_bf16 v[60:63], v[100:103], v[164:167], v[60:63]
	v_mfma_f32_16x16x32_bf16 v[56:59], v[116:119], v[164:167], v[56:59]
	v_mfma_f32_16x16x32_bf16 v[44:47], v[100:103], v[186:189], v[44:47]
	v_mfma_f32_16x16x32_bf16 v[40:43], v[116:119], v[186:189], v[40:43]
	v_mfma_f32_16x16x32_bf16 v[28:31], v[100:103], v[204:207], v[28:31]
	v_mfma_f32_16x16x32_bf16 v[24:27], v[116:119], v[204:207], v[24:27]
	v_mfma_f32_16x16x32_bf16 v[12:15], v[100:103], v[212:215], v[12:15]
	v_mfma_f32_16x16x32_bf16 v[8:11], v[116:119], v[212:215], v[8:11]
	v_mfma_f32_16x16x32_bf16 v[52:55], v[144:147], v[160:163], v[52:55]
	v_mfma_f32_16x16x32_bf16 v[48:51], v[152:155], v[160:163], v[48:51]
	v_mfma_f32_16x16x32_bf16 v[36:39], v[144:147], v[182:185], v[36:39]
	v_mfma_f32_16x16x32_bf16 v[32:35], v[152:155], v[182:185], v[32:35]
	v_mfma_f32_16x16x32_bf16 v[20:23], v[144:147], v[194:197], v[20:23]
	v_mfma_f32_16x16x32_bf16 v[16:19], v[152:155], v[194:197], v[16:19]
	v_mfma_f32_16x16x32_bf16 v[4:7], v[144:147], v[208:211], v[4:7]
	v_mfma_f32_16x16x32_bf16 v[0:3], v[152:155], v[208:211], v[0:3]
	v_mfma_f32_16x16x32_bf16 v[52:55], v[148:151], v[164:167], v[52:55]
	v_mfma_f32_16x16x32_bf16 v[48:51], v[156:159], v[164:167], v[48:51]
	v_mfma_f32_16x16x32_bf16 v[36:39], v[148:151], v[186:189], v[36:39]
	v_mfma_f32_16x16x32_bf16 v[32:35], v[156:159], v[186:189], v[32:35]
	v_mfma_f32_16x16x32_bf16 v[20:23], v[148:151], v[204:207], v[20:23]
	v_mfma_f32_16x16x32_bf16 v[16:19], v[156:159], v[204:207], v[16:19]
	v_mfma_f32_16x16x32_bf16 v[4:7], v[148:151], v[212:215], v[4:7]
	v_mfma_f32_16x16x32_bf16 v[0:3], v[156:159], v[212:215], v[0:3]
	s_barrier
	s_setprio 0
	s_add_u32 s42, s42, 0x100
	s_addc_u32 s43, s43, 0
	s_add_u32 s83, s83, 0x100
	s_addc_u32 s84, s84, 0
	s_cmp_ge_u32 s85, s70
	s_mov_b32 s46, s85
	s_cbranch_scc0 .LBB0_1079
	s_and_b64 vcc, exec, s[18:19]
	s_cbranch_vccz .LBB0_1082
	s_barrier
